# P5 up-GEMM epilogue: row_rstd partial loads hoisted, 8 rows reduced together, acc pre-scaled; serialized chains removed
# speedup vs baseline: 1.0081x; 1.0009x over previous
; #define PG8_STAGE(bufoff, gbase, voff) do { _Pragma("unroll") for (int _i = 0; _i < 2; ++_i) \
;         __builtin_amdgcn_global_load_lds((const __attribute__((address_space(1))) unsigned*)((const char*)(gbase) + (voff)[_i]), (LAS unsigned*)(lds + (bufoff) + ldsw + _i * 8192), 16, 0, 0); } while (0)
; #define PG8_LDA(dst, b, h) do { _Pragma("unroll") for (int m = 0; m < 4; ++m) _Pragma("unroll") for (int k = 0; k < 2; ++k) dst[m][k] = *(const LAS bf16x8*)(lds + PG8_SA(b, h) + aoff + m * 2048 + k * 1024); } while (0)
; #define PG8_LDB(dst, b, h) do { _Pragma("unroll") for (int n = 0; n < 2; ++n) _Pragma("unroll") for (int k = 0; k < 2; ++k) dst[n][k] = *(const LAS bf16x8*)(lds + PG8_SB(b, h) + boff + n * 2048 + k * 1024); } while (0)
; #define PG8_MMA(ai, bj, At, Bt) do { __builtin_amdgcn_s_setprio(1); _Pragma("unroll") for (int m = 0; m < 4; ++m) _Pragma("unroll") for (int n = 0; n < 2; ++n) _Pragma("unroll") for (int k = 0; k < 2; ++k) \
;         acc[ai][bj][m][n] = __builtin_amdgcn_mfma_f32_16x16x32_bf16(Bt[n][k], At[m][k], acc[ai][bj][m][n], 0, 0, 0); __builtin_amdgcn_s_setprio(0); } while (0)
; #define PG8_BAR __builtin_amdgcn_s_barrier()
; template <class Epi, class SchedT, bool ALIGN_EPI, bool SP2>
; __device__ __forceinline__ void gemm_phase(LAS unsigned char* lds, const int ldk, const int nt, const SchedT& S, const Epi& E) {
;     ...
;             PG8_LDB(B0, 0, 0); PG8_LDB(B1, 0, 1); PG8_SCHED; PG8_LDA(At, 0, 0); PG8_STAGE(PG8_SA(1, 1), a1 + hstep, voffA);
;             PG8_WAIT_V(8); PG8_WAIT_L(0); PG8_BAR; PG8_MMA(0, 0, At, B0); PG8_MMA(0, 1, At, B1); PG8_BAR; PG8_SCHED;
;             PG8_LDA(At, 0, 1); PG8_STAGE(PG8_SB(0, 0), b2, voffB); PG8_STAGE(PG8_SB(0, 1), b2 + hstepB, voffB); PG8_STAGE(PG8_SA(0, 0), a2, voffA);
;             PG8_WAIT_V(8); PG8_WAIT_L(0); PG8_BAR; PG8_MMA(1, 0, At, B0); PG8_MMA(1, 1, At, B1); PG8_BAR; PG8_SCHED;
;             PG8_LDB(B0, 1, 0); PG8_LDB(B1, 1, 1); PG8_SCHED; PG8_LDA(At, 1, 0); PG8_STAGE(PG8_SA(0, 1), a2 + hstep, voffA);
;             PG8_WAIT_V(8); PG8_WAIT_L(0); PG8_BAR; PG8_MMA(0, 0, At, B0); PG8_MMA(0, 1, At, B1); PG8_BAR; PG8_SCHED;
;             PG8_LDA(At, 1, 1); PG8_STAGE(PG8_SB(1, 0), b3, voffB); PG8_STAGE(PG8_SB(1, 1), b3 + hstepB, voffB); PG8_STAGE(PG8_SA(1, 0), a3, voffA);
;             PG8_WAIT_V(8); PG8_WAIT_L(0); PG8_BAR; PG8_MMA(1, 0, At, B0); PG8_MMA(1, 1, At, B1); PG8_BAR; PG8_SCHED;
.LBB0_752:
	s_add_u32 s36, s34, 0xfff80080
	s_addc_u32 s37, s35, -1
	s_add_i32 s61, 0, 0x10000
	s_cmp_eq_u32 s59, 28
	s_cselect_b32 vcc_hi, s1, s37
	s_cselect_b32 vcc_lo, s0, s36
	s_cselect_b32 s37, s63, s17
	s_cselect_b32 s36, s62, s13
	s_add_i32 s64, 0, 0x14000
	v_add_u32_e32 v142, s61, v248
	v_add_u32_e32 v182, s64, v248
	ds_read_b128 v[130:133], v142
	ds_read_b128 v[134:137], v142 offset:1024
	ds_read_b128 v[138:141], v142 offset:2048
	ds_read_b128 v[142:145], v142 offset:3072
	ds_read_b128 v[158:161], v182
	ds_read_b128 v[174:177], v182 offset:1024
	ds_read_b128 v[178:181], v182 offset:2048
	ds_read_b128 v[182:185], v182 offset:3072
	v_lshl_add_u64 v[218:219], v[222:223], 0, s[24:25]
	s_mov_b32 m0, s89
	s_nop 0
	global_load_lds_dwordx4 v[218:219], off
	v_lshl_add_u64 v[218:219], v[224:225], 0, s[24:25]
	s_mov_b32 m0, s90
	s_nop 0
	global_load_lds_dwordx4 v[218:219], off
	v_lshl_add_u64 v[218:219], s[34:35], 0, v[154:155]
	s_add_i32 m0, s85, 0xc000
	ds_read_b128 v[186:189], v251
	ds_read_b128 v[190:193], v251 offset:1024
	ds_read_b128 v[194:197], v251 offset:2048
	ds_read_b128 v[198:201], v251 offset:3072
	ds_read_b128 v[202:205], v251 offset:4096
	ds_read_b128 v[206:209], v251 offset:5120
	ds_read_b128 v[210:213], v251 offset:6144
	ds_read_b128 v[214:217], v251 offset:7168
	global_load_lds_dwordx4 v[218:219], off
	v_lshl_add_u64 v[218:219], s[34:35], 0, v[156:157]
	s_add_i32 m0, s85, 0xe000
	s_nop 0
	global_load_lds_dwordx4 v[218:219], off
	s_nop 0
	s_nop 0
	s_nop 0
	s_waitcnt vmcnt(8)
	s_waitcnt lgkmcnt(0)
	s_barrier
	s_setprio 1
	s_waitcnt lgkmcnt(0)
	v_mfma_f32_16x16x32_bf16 v[126:129], v[130:133], v[186:189], v[126:129]
	v_mfma_f32_16x16x32_bf16 v[62:65], v[138:141], v[186:189], v[62:65]
	v_mfma_f32_16x16x32_bf16 v[118:121], v[130:133], v[194:197], v[118:121]
	v_mfma_f32_16x16x32_bf16 v[58:61], v[138:141], v[194:197], v[58:61]
	v_mfma_f32_16x16x32_bf16 v[110:113], v[130:133], v[202:205], v[110:113]
	v_mfma_f32_16x16x32_bf16 v[46:49], v[138:141], v[202:205], v[46:49]
	v_mfma_f32_16x16x32_bf16 v[106:109], v[130:133], v[210:213], v[106:109]
	v_mfma_f32_16x16x32_bf16 v[42:45], v[138:141], v[210:213], v[42:45]
	v_mfma_f32_16x16x32_bf16 v[126:129], v[134:137], v[190:193], v[126:129]
	v_mfma_f32_16x16x32_bf16 v[62:65], v[142:145], v[190:193], v[62:65]
	v_mfma_f32_16x16x32_bf16 v[118:121], v[134:137], v[198:201], v[118:121]
	v_mfma_f32_16x16x32_bf16 v[58:61], v[142:145], v[198:201], v[58:61]
	v_mfma_f32_16x16x32_bf16 v[110:113], v[134:137], v[206:209], v[110:113]
	v_mfma_f32_16x16x32_bf16 v[46:49], v[142:145], v[206:209], v[46:49]
	v_mfma_f32_16x16x32_bf16 v[106:109], v[134:137], v[214:217], v[106:109]
	v_mfma_f32_16x16x32_bf16 v[42:45], v[142:145], v[214:217], v[42:45]
	s_setprio 0
	s_setprio 1
	v_mfma_f32_16x16x32_bf16 v[122:125], v[158:161], v[186:189], v[122:125]
	v_mfma_f32_16x16x32_bf16 v[54:57], v[178:181], v[186:189], v[54:57]
	v_mfma_f32_16x16x32_bf16 v[114:117], v[158:161], v[194:197], v[114:117]
	v_mfma_f32_16x16x32_bf16 v[50:53], v[178:181], v[194:197], v[50:53]
	v_mfma_f32_16x16x32_bf16 v[102:105], v[158:161], v[202:205], v[102:105]
	v_mfma_f32_16x16x32_bf16 v[38:41], v[178:181], v[202:205], v[38:41]
	v_mfma_f32_16x16x32_bf16 v[98:101], v[158:161], v[210:213], v[98:101]
	v_mfma_f32_16x16x32_bf16 v[34:37], v[178:181], v[210:213], v[34:37]
	v_mfma_f32_16x16x32_bf16 v[122:125], v[174:177], v[190:193], v[122:125]
	v_mfma_f32_16x16x32_bf16 v[54:57], v[182:185], v[190:193], v[54:57]
	v_mfma_f32_16x16x32_bf16 v[114:117], v[174:177], v[198:201], v[114:117]
	v_mfma_f32_16x16x32_bf16 v[50:53], v[182:185], v[198:201], v[50:53]
	v_mfma_f32_16x16x32_bf16 v[102:105], v[174:177], v[206:209], v[102:105]
	v_mfma_f32_16x16x32_bf16 v[38:41], v[182:185], v[206:209], v[38:41]
	v_mfma_f32_16x16x32_bf16 v[98:101], v[174:177], v[214:217], v[98:101]
	v_mfma_f32_16x16x32_bf16 v[34:37], v[182:185], v[214:217], v[34:37]
	s_setprio 0
	s_barrier
	s_add_i32 s61, s61, s84
	v_lshl_add_u64 v[218:219], s[36:37], 0, v[0:1]
	s_mov_b32 m0, s61
	ds_read_b128 v[186:189], v251 offset:16384
	ds_read_b128 v[190:193], v251 offset:17408
	ds_read_b128 v[194:197], v251 offset:18432
	ds_read_b128 v[198:201], v251 offset:19456
	ds_read_b128 v[202:205], v251 offset:20480
	ds_read_b128 v[206:209], v251 offset:21504
	ds_read_b128 v[210:213], v251 offset:22528
	ds_read_b128 v[214:217], v251 offset:23552
	global_load_lds_dwordx4 v[218:219], off
	s_add_i32 m0, s61, 0x2000
	s_add_u32 s94, s36, 0x20000
	v_lshl_add_u64 v[220:221], s[36:37], 0, v[150:151]
	s_addc_u32 s95, s37, 0
	s_add_i32 s61, s64, s84
	global_load_lds_dwordx4 v[220:221], off
	v_lshl_add_u64 v[222:223], s[94:95], 0, v[0:1]
	s_mov_b32 m0, s61
	v_lshl_add_u64 v[224:225], vcc, 0, v[148:149]
	global_load_lds_dwordx4 v[222:223], off
	v_lshl_add_u64 v[222:223], s[94:95], 0, v[150:151]
	s_add_i32 m0, s61, 0x2000
	s_nop 0
	global_load_lds_dwordx4 v[222:223], off
	v_lshl_add_u64 v[222:223], vcc, 0, v[146:147]
	s_nop 0
	s_waitcnt vmcnt(6)
	s_waitcnt lgkmcnt(0)
	s_barrier
; #define PG8_STAGE(bufoff, gbase, voff) do { _Pragma("unroll") for (int _i = 0; _i < 2; ++_i) \
;         __builtin_amdgcn_global_load_lds((const __attribute__((address_space(1))) unsigned*)((const char*)(gbase) + (voff)[_i]), (LAS unsigned*)(lds + (bufoff) + ldsw + _i * 8192), 16, 0, 0); } while (0)
; #define PG8_LDA(dst, b, h) do { _Pragma("unroll") for (int m = 0; m < 4; ++m) _Pragma("unroll") for (int k = 0; k < 2; ++k) dst[m][k] = *(const LAS bf16x8*)(lds + PG8_SA(b, h) + aoff + m * 2048 + k * 1024); } while (0)
; #define PG8_LDB(dst, b, h) do { _Pragma("unroll") for (int n = 0; n < 2; ++n) _Pragma("unroll") for (int k = 0; k < 2; ++k) dst[n][k] = *(const LAS bf16x8*)(lds + PG8_SB(b, h) + boff + n * 2048 + k * 1024); } while (0)
; #define PG8_MMA(ai, bj, At, Bt) do { __builtin_amdgcn_s_setprio(1); _Pragma("unroll") for (int m = 0; m < 4; ++m) _Pragma("unroll") for (int n = 0; n < 2; ++n) _Pragma("unroll") for (int k = 0; k < 2; ++k) \
;         acc[ai][bj][m][n] = __builtin_amdgcn_mfma_f32_16x16x32_bf16(Bt[n][k], At[m][k], acc[ai][bj][m][n], 0, 0, 0); __builtin_amdgcn_s_setprio(0); } while (0)
; #define PG8_BAR __builtin_amdgcn_s_barrier()
; template <class Epi, class SchedT, bool ALIGN_EPI, bool SP2>
; __device__ __forceinline__ void gemm_phase(LAS unsigned char* lds, const int ldk, const int nt, const SchedT& S, const Epi& E) {
;     ...
;             PG8_LDB(B0, 0, 0); PG8_LDB(B1, 0, 1); PG8_SCHED; PG8_LDA(At, 0, 0); PG8_STAGE(PG8_SA(1, 1), a1 + hstep, voffA);
;             PG8_WAIT_V(8); PG8_WAIT_L(0); PG8_BAR; PG8_MMA(0, 0, At, B0); PG8_MMA(0, 1, At, B1); PG8_BAR; PG8_SCHED;
;             PG8_LDA(At, 0, 1); PG8_STAGE(PG8_SB(0, 0), b2, voffB); PG8_STAGE(PG8_SB(0, 1), b2 + hstepB, voffB); PG8_STAGE(PG8_SA(0, 0), a2, voffA);
;             PG8_WAIT_V(8); PG8_WAIT_L(0); PG8_BAR; PG8_MMA(1, 0, At, B0); PG8_MMA(1, 1, At, B1); PG8_BAR; PG8_SCHED;
;             PG8_LDB(B0, 1, 0); PG8_LDB(B1, 1, 1); PG8_SCHED; PG8_LDA(At, 1, 0); PG8_STAGE(PG8_SA(0, 1), a2 + hstep, voffA);
;             PG8_WAIT_V(8); PG8_WAIT_L(0); PG8_BAR; PG8_MMA(0, 0, At, B0); PG8_MMA(0, 1, At, B1); PG8_BAR; PG8_SCHED;
;             PG8_LDA(At, 1, 1); PG8_STAGE(PG8_SB(1, 0), b3, voffB); PG8_STAGE(PG8_SB(1, 1), b3 + hstepB, voffB); PG8_STAGE(PG8_SA(1, 0), a3, voffA);
;             PG8_WAIT_V(8); PG8_WAIT_L(0); PG8_BAR; PG8_MMA(1, 0, At, B0); PG8_MMA(1, 1, At, B1); PG8_BAR; PG8_SCHED;
	s_setprio 1
	s_waitcnt lgkmcnt(0)
	v_mfma_f32_16x16x32_bf16 v[94:97], v[130:133], v[186:189], v[94:97]
	v_mfma_f32_16x16x32_bf16 v[30:33], v[138:141], v[186:189], v[30:33]
	v_mfma_f32_16x16x32_bf16 v[90:93], v[130:133], v[194:197], v[90:93]
	v_mfma_f32_16x16x32_bf16 v[26:29], v[138:141], v[194:197], v[26:29]
	v_mfma_f32_16x16x32_bf16 v[78:81], v[130:133], v[202:205], v[78:81]
	v_mfma_f32_16x16x32_bf16 v[14:17], v[138:141], v[202:205], v[14:17]
	v_mfma_f32_16x16x32_bf16 v[74:77], v[130:133], v[210:213], v[74:77]
	v_mfma_f32_16x16x32_bf16 v[10:13], v[138:141], v[210:213], v[10:13]
	v_mfma_f32_16x16x32_bf16 v[94:97], v[134:137], v[190:193], v[94:97]
	v_mfma_f32_16x16x32_bf16 v[30:33], v[142:145], v[190:193], v[30:33]
	v_mfma_f32_16x16x32_bf16 v[90:93], v[134:137], v[198:201], v[90:93]
	v_mfma_f32_16x16x32_bf16 v[26:29], v[142:145], v[198:201], v[26:29]
	v_mfma_f32_16x16x32_bf16 v[78:81], v[134:137], v[206:209], v[78:81]
	v_mfma_f32_16x16x32_bf16 v[14:17], v[142:145], v[206:209], v[14:17]
	v_mfma_f32_16x16x32_bf16 v[74:77], v[134:137], v[214:217], v[74:77]
	v_mfma_f32_16x16x32_bf16 v[10:13], v[142:145], v[214:217], v[10:13]
	s_setprio 0
	s_setprio 1
	v_mfma_f32_16x16x32_bf16 v[86:89], v[158:161], v[186:189], v[86:89]
	v_mfma_f32_16x16x32_bf16 v[22:25], v[178:181], v[186:189], v[22:25]
	v_mfma_f32_16x16x32_bf16 v[82:85], v[158:161], v[194:197], v[82:85]
	v_mfma_f32_16x16x32_bf16 v[18:21], v[178:181], v[194:197], v[18:21]
	v_mfma_f32_16x16x32_bf16 v[70:73], v[158:161], v[202:205], v[70:73]
	v_mfma_f32_16x16x32_bf16 v[6:9], v[178:181], v[202:205], v[6:9]
	v_mfma_f32_16x16x32_bf16 v[66:69], v[158:161], v[210:213], v[66:69]
	v_mfma_f32_16x16x32_bf16 v[2:5], v[178:181], v[210:213], v[2:5]
	v_mfma_f32_16x16x32_bf16 v[86:89], v[174:177], v[190:193], v[86:89]
	v_mfma_f32_16x16x32_bf16 v[22:25], v[182:185], v[190:193], v[22:25]
	v_mfma_f32_16x16x32_bf16 v[82:85], v[174:177], v[198:201], v[82:85]
	v_mfma_f32_16x16x32_bf16 v[18:21], v[182:185], v[198:201], v[18:21]
	v_mfma_f32_16x16x32_bf16 v[70:73], v[174:177], v[206:209], v[70:73]
	v_mfma_f32_16x16x32_bf16 v[6:9], v[182:185], v[206:209], v[6:9]
	v_mfma_f32_16x16x32_bf16 v[66:69], v[174:177], v[214:217], v[66:69]
	v_mfma_f32_16x16x32_bf16 v[2:5], v[182:185], v[214:217], v[2:5]
	s_setprio 0
	s_barrier
	s_add_i32 s61, 0, 0x18000
	s_add_i32 s64, 0, 0x1c000
	v_add_u32_e32 v142, s61, v248
	v_add_u32_e32 v182, s64, v248
	ds_read_b128 v[130:133], v142
	ds_read_b128 v[134:137], v142 offset:1024
	ds_read_b128 v[138:141], v142 offset:2048
	ds_read_b128 v[142:145], v142 offset:3072
	ds_read_b128 v[158:161], v182
	ds_read_b128 v[174:177], v182 offset:1024
	ds_read_b128 v[178:181], v182 offset:2048
	ds_read_b128 v[182:185], v182 offset:3072
	s_add_u32 s94, vcc_lo, 0x80000
	s_addc_u32 s95, vcc_hi, 0
	s_mov_b32 m0, s85
	s_nop 0
	global_load_lds_dwordx4 v[222:223], off
	s_mov_b32 m0, s86
	s_nop 0
	global_load_lds_dwordx4 v[224:225], off
	s_mov_b32 m0, s87
	v_lshl_add_u64 v[226:227], s[94:95], 0, v[146:147]
	ds_read_b128 v[186:189], v251 offset:32768
	ds_read_b128 v[190:193], v251 offset:33792
	ds_read_b128 v[194:197], v251 offset:34816
	ds_read_b128 v[198:201], v251 offset:35840
	ds_read_b128 v[202:205], v251 offset:36864
	ds_read_b128 v[206:209], v251 offset:37888
	ds_read_b128 v[210:213], v251 offset:38912
	ds_read_b128 v[214:217], v251 offset:39936
	global_load_lds_dwordx4 v[226:227], off
	v_lshl_add_u64 v[226:227], s[94:95], 0, v[148:149]
	s_mov_b32 m0, s88
	s_nop 0
	global_load_lds_dwordx4 v[226:227], off
	s_nop 0
	s_waitcnt vmcnt(8)
	s_waitcnt lgkmcnt(0)
	s_barrier
	s_setprio 1
	s_waitcnt lgkmcnt(0)
	v_mfma_f32_16x16x32_bf16 v[126:129], v[130:133], v[186:189], v[126:129]
	v_mfma_f32_16x16x32_bf16 v[62:65], v[138:141], v[186:189], v[62:65]
	v_mfma_f32_16x16x32_bf16 v[118:121], v[130:133], v[194:197], v[118:121]
	v_mfma_f32_16x16x32_bf16 v[58:61], v[138:141], v[194:197], v[58:61]
	v_mfma_f32_16x16x32_bf16 v[110:113], v[130:133], v[202:205], v[110:113]
	v_mfma_f32_16x16x32_bf16 v[46:49], v[138:141], v[202:205], v[46:49]
	v_mfma_f32_16x16x32_bf16 v[106:109], v[130:133], v[210:213], v[106:109]
	v_mfma_f32_16x16x32_bf16 v[42:45], v[138:141], v[210:213], v[42:45]
	v_mfma_f32_16x16x32_bf16 v[126:129], v[134:137], v[190:193], v[126:129]
	v_mfma_f32_16x16x32_bf16 v[62:65], v[142:145], v[190:193], v[62:65]
	v_mfma_f32_16x16x32_bf16 v[118:121], v[134:137], v[198:201], v[118:121]
	v_mfma_f32_16x16x32_bf16 v[58:61], v[142:145], v[198:201], v[58:61]
	v_mfma_f32_16x16x32_bf16 v[110:113], v[134:137], v[206:209], v[110:113]
	v_mfma_f32_16x16x32_bf16 v[46:49], v[142:145], v[206:209], v[46:49]
	v_mfma_f32_16x16x32_bf16 v[106:109], v[134:137], v[214:217], v[106:109]
	v_mfma_f32_16x16x32_bf16 v[42:45], v[142:145], v[214:217], v[42:45]
	s_setprio 0
	s_setprio 1
	v_mfma_f32_16x16x32_bf16 v[122:125], v[158:161], v[186:189], v[122:125]
	v_mfma_f32_16x16x32_bf16 v[54:57], v[178:181], v[186:189], v[54:57]
	v_mfma_f32_16x16x32_bf16 v[114:117], v[158:161], v[194:197], v[114:117]
	v_mfma_f32_16x16x32_bf16 v[50:53], v[178:181], v[194:197], v[50:53]
	v_mfma_f32_16x16x32_bf16 v[102:105], v[158:161], v[202:205], v[102:105]
	v_mfma_f32_16x16x32_bf16 v[38:41], v[178:181], v[202:205], v[38:41]
	v_mfma_f32_16x16x32_bf16 v[98:101], v[158:161], v[210:213], v[98:101]
	v_mfma_f32_16x16x32_bf16 v[34:37], v[178:181], v[210:213], v[34:37]
	v_mfma_f32_16x16x32_bf16 v[122:125], v[174:177], v[190:193], v[122:125]
	v_mfma_f32_16x16x32_bf16 v[54:57], v[182:185], v[190:193], v[54:57]
	v_mfma_f32_16x16x32_bf16 v[114:117], v[174:177], v[198:201], v[114:117]
	v_mfma_f32_16x16x32_bf16 v[50:53], v[182:185], v[198:201], v[50:53]
	v_mfma_f32_16x16x32_bf16 v[102:105], v[174:177], v[206:209], v[102:105]
	v_mfma_f32_16x16x32_bf16 v[38:41], v[182:185], v[206:209], v[38:41]
	v_mfma_f32_16x16x32_bf16 v[98:101], v[174:177], v[214:217], v[98:101]
	v_mfma_f32_16x16x32_bf16 v[34:37], v[182:185], v[214:217], v[34:37]
	s_setprio 0
	s_barrier
; #define PG8_STAGE(bufoff, gbase, voff) do { _Pragma("unroll") for (int _i = 0; _i < 2; ++_i) \
;         __builtin_amdgcn_global_load_lds((const __attribute__((address_space(1))) unsigned*)((const char*)(gbase) + (voff)[_i]), (LAS unsigned*)(lds + (bufoff) + ldsw + _i * 8192), 16, 0, 0); } while (0)
; #define PG8_LDA(dst, b, h) do { _Pragma("unroll") for (int m = 0; m < 4; ++m) _Pragma("unroll") for (int k = 0; k < 2; ++k) dst[m][k] = *(const LAS bf16x8*)(lds + PG8_SA(b, h) + aoff + m * 2048 + k * 1024); } while (0)
; #define PG8_LDB(dst, b, h) do { _Pragma("unroll") for (int n = 0; n < 2; ++n) _Pragma("unroll") for (int k = 0; k < 2; ++k) dst[n][k] = *(const LAS bf16x8*)(lds + PG8_SB(b, h) + boff + n * 2048 + k * 1024); } while (0)
; #define PG8_WAIT_V(n) asm volatile("s_waitcnt vmcnt(" #n ")" ::: "memory")
; #define PG8_WAIT_L(n) asm volatile("s_waitcnt lgkmcnt(" #n ")" ::: "memory")
; #define PG8_BAR __builtin_amdgcn_s_barrier()
; #define PG8_SCHED __builtin_amdgcn_sched_barrier(0)
; __device__ __forceinline__ float row_rstd(const float* ssp, int row, int fq) {
;     const f32x4 a = *(const f32x4*)(ssp + (size_t)row * 32 + 8 * fq), b = *(const f32x4*)(ssp + (size_t)row * 32 + 8 * fq + 4);
; template <class Epi, class SchedT, bool ALIGN_EPI, bool SP2>
; __device__ __forceinline__ void gemm_phase(LAS unsigned char* lds, const int ldk, const int nt, const SchedT& S, const Epi& E) {
;     ...
;             PG8_WAIT_V(8); PG8_WAIT_L(0); PG8_BAR; PG8_MMA(0, 0, At, B0); PG8_MMA(0, 1, At, B1); PG8_BAR; PG8_SCHED;
;             PG8_LDA(At, 0, 1); PG8_STAGE(PG8_SB(0, 0), b2, voffB); PG8_STAGE(PG8_SB(0, 1), b2 + hstepB, voffB); PG8_STAGE(PG8_SA(0, 0), a2, voffA);
;             PG8_WAIT_V(8); PG8_WAIT_L(0); PG8_BAR; PG8_MMA(1, 0, At, B0); PG8_MMA(1, 1, At, B1); PG8_BAR; PG8_SCHED;
;             PG8_LDB(B0, 1, 0); PG8_LDB(B1, 1, 1); PG8_SCHED; PG8_LDA(At, 1, 0); PG8_STAGE(PG8_SA(0, 1), a2 + hstep, voffA);
;             PG8_WAIT_V(8); PG8_WAIT_L(0); PG8_BAR; PG8_MMA(0, 0, At, B0); PG8_MMA(0, 1, At, B1); PG8_BAR; PG8_SCHED;
;             PG8_LDA(At, 1, 1); PG8_STAGE(PG8_SB(1, 0), b3, voffB); PG8_STAGE(PG8_SB(1, 1), b3 + hstepB, voffB); PG8_STAGE(PG8_SA(1, 0), a3, voffA);
;             PG8_WAIT_V(8); PG8_WAIT_L(0); PG8_BAR; PG8_MMA(1, 0, At, B0); PG8_MMA(1, 1, At, B1); PG8_BAR; PG8_SCHED;
	s_add_i32 s61, s61, s84
	v_lshl_add_u64 v[218:219], v[218:219], 0, s[24:25]
	s_mov_b32 m0, s61
	ds_read_b128 v[186:189], v251 offset:49152
	ds_read_b128 v[190:193], v251 offset:50176
	ds_read_b128 v[194:197], v251 offset:51200
	ds_read_b128 v[198:201], v251 offset:52224
	ds_read_b128 v[202:205], v251 offset:53248
	ds_read_b128 v[206:209], v251 offset:54272
	ds_read_b128 v[210:213], v251 offset:55296
	ds_read_b128 v[214:217], v251 offset:56320
	global_load_lds_dwordx4 v[218:219], off
	s_add_i32 m0, s61, 0x2000
	s_add_u32 s36, s36, 0x20080
	v_lshl_add_u64 v[218:219], v[220:221], 0, s[24:25]
	s_addc_u32 s37, s37, 0
	s_add_i32 s61, s64, s84
	global_load_lds_dwordx4 v[218:219], off
	v_lshl_add_u64 v[218:219], s[36:37], 0, v[0:1]
	s_mov_b32 m0, s61
	s_nop 0
	global_load_lds_dwordx4 v[218:219], off
	v_lshl_add_u64 v[218:219], s[36:37], 0, v[150:151]
	s_add_i32 m0, s61, 0x2000
	s_nop 0
	global_load_lds_dwordx4 v[218:219], off
	s_waitcnt vmcnt(6)
	s_waitcnt lgkmcnt(0)
	s_barrier
	s_setprio 1
	s_waitcnt lgkmcnt(0)
	v_mfma_f32_16x16x32_bf16 v[94:97], v[130:133], v[186:189], v[94:97]
	v_mfma_f32_16x16x32_bf16 v[30:33], v[138:141], v[186:189], v[30:33]
	v_mfma_f32_16x16x32_bf16 v[90:93], v[130:133], v[194:197], v[90:93]
	v_mfma_f32_16x16x32_bf16 v[26:29], v[138:141], v[194:197], v[26:29]
	v_mfma_f32_16x16x32_bf16 v[78:81], v[130:133], v[202:205], v[78:81]
	v_mfma_f32_16x16x32_bf16 v[14:17], v[138:141], v[202:205], v[14:17]
	v_mfma_f32_16x16x32_bf16 v[74:77], v[130:133], v[210:213], v[74:77]
	v_mfma_f32_16x16x32_bf16 v[10:13], v[138:141], v[210:213], v[10:13]
	v_mfma_f32_16x16x32_bf16 v[94:97], v[134:137], v[190:193], v[94:97]
	v_mfma_f32_16x16x32_bf16 v[30:33], v[142:145], v[190:193], v[30:33]
	v_mfma_f32_16x16x32_bf16 v[90:93], v[134:137], v[198:201], v[90:93]
	v_mfma_f32_16x16x32_bf16 v[26:29], v[142:145], v[198:201], v[26:29]
	v_mfma_f32_16x16x32_bf16 v[78:81], v[134:137], v[206:209], v[78:81]
	v_mfma_f32_16x16x32_bf16 v[14:17], v[142:145], v[206:209], v[14:17]
	v_mfma_f32_16x16x32_bf16 v[74:77], v[134:137], v[214:217], v[74:77]
	v_mfma_f32_16x16x32_bf16 v[10:13], v[142:145], v[214:217], v[10:13]
	s_setprio 0
	s_setprio 1
	v_mfma_f32_16x16x32_bf16 v[86:89], v[158:161], v[186:189], v[86:89]
	v_mfma_f32_16x16x32_bf16 v[22:25], v[178:181], v[186:189], v[22:25]
	v_mfma_f32_16x16x32_bf16 v[82:85], v[158:161], v[194:197], v[82:85]
	v_mfma_f32_16x16x32_bf16 v[18:21], v[178:181], v[194:197], v[18:21]
	v_mfma_f32_16x16x32_bf16 v[70:73], v[158:161], v[202:205], v[70:73]
	v_mfma_f32_16x16x32_bf16 v[6:9], v[178:181], v[202:205], v[6:9]
	v_mfma_f32_16x16x32_bf16 v[66:69], v[158:161], v[210:213], v[66:69]
	v_mfma_f32_16x16x32_bf16 v[2:5], v[178:181], v[210:213], v[2:5]
	v_mfma_f32_16x16x32_bf16 v[86:89], v[174:177], v[190:193], v[86:89]
	v_mfma_f32_16x16x32_bf16 v[22:25], v[182:185], v[190:193], v[22:25]
	v_mfma_f32_16x16x32_bf16 v[82:85], v[174:177], v[198:201], v[82:85]
	v_mfma_f32_16x16x32_bf16 v[18:21], v[182:185], v[198:201], v[18:21]
	v_mfma_f32_16x16x32_bf16 v[70:73], v[174:177], v[206:209], v[70:73]
	v_mfma_f32_16x16x32_bf16 v[6:9], v[182:185], v[206:209], v[6:9]
	v_mfma_f32_16x16x32_bf16 v[66:69], v[174:177], v[214:217], v[66:69]
	v_mfma_f32_16x16x32_bf16 v[2:5], v[182:185], v[214:217], v[2:5]
	s_setprio 0
	s_barrier
	s_add_i32 s59, s59, 2
	s_add_u32 s34, s34, 0x100
	s_addc_u32 s35, s35, 0
	s_add_u32 s13, s13, 0x100
	s_addc_u32 s17, s17, 0
	s_cmp_gt_u32 s59, 29
	s_cbranch_scc0 .LBB0_752
	v_lshl_add_u32 v130, s12, 8, v247
	v_lshlrev_b32_e32 v140, 7, v130
	v_mov_b32_e32 v141, 0
	v_lshl_add_u64 v[132:133], v[152:153], 0, v[140:141]
	v_add_u32_e32 v140, 0x1000, v140
	v_lshl_add_u64 v[134:135], v[152:153], 0, v[140:141]
	v_add_u32_e32 v140, 0x3000, v140
	v_lshl_add_u64 v[136:137], v[152:153], 0, v[140:141]
	v_add_u32_e32 v140, 0x1000, v140
	v_lshl_add_u64 v[138:139], v[152:153], 0, v[140:141]
	global_load_dwordx4 v[174:177], v[132:133], off
	global_load_dwordx4 v[178:181], v[132:133], off offset:16
	global_load_dwordx4 v[182:185], v[132:133], off offset:2048
	global_load_dwordx4 v[186:189], v[132:133], off offset:2064
	global_load_dwordx4 v[190:193], v[134:135], off
	global_load_dwordx4 v[194:197], v[134:135], off offset:16
	global_load_dwordx4 v[198:201], v[134:135], off offset:2048
	global_load_dwordx4 v[202:205], v[134:135], off offset:2064
	global_load_dwordx4 v[206:209], v[136:137], off
	global_load_dwordx4 v[210:213], v[136:137], off offset:16
	global_load_dwordx4 v[214:217], v[136:137], off offset:2048
	global_load_dwordx4 v[218:221], v[136:137], off offset:2064
	global_load_dwordx4 v[222:225], v[138:139], off
	global_load_dwordx4 v[226:229], v[138:139], off offset:16
	global_load_dwordx4 v[230:233], v[138:139], off offset:2048
	global_load_dwordx4 v[234:237], v[138:139], off offset:2064
	v_xor_b32_e32 v238, 16, v241
	v_xor_b32_e32 v239, 32, v241
	v_lshlrev_b32_e32 v238, 2, v238
	v_lshlrev_b32_e32 v239, 2, v239
	s_and_b64 vcc, exec, s[56:57]
	s_cbranch_vccz .LBB0_755
	s_barrier
; __device__ __forceinline__ float row_rstd(const float* ssp, int row, int fq) {
;     const f32x4 a = *(const f32x4*)(ssp + (size_t)row * 32 + 8 * fq), b = *(const f32x4*)(ssp + (size_t)row * 32 + 8 * fq + 4);
;     float s = ((a[0] + a[1]) + (a[2] + a[3])) + ((b[0] + b[1]) + (b[2] + b[3]));
;     s += __shfl_xor(s, 16); s += __shfl_xor(s, 32);
;     return __builtin_amdgcn_rsqf(s * (1.0f / 2048.0f) + 1e-6f);
;     __device__ __forceinline__ void operator()(f32x4 (&acc)[2][2][4][2], const Unit& u, int wr, int wc, int fr, int fq) const {
;     ...
;         for (int ai = 0; ai < 2; ++ai)
; #pragma unroll
;             for (int m = 0; m < 4; ++m) { const float rstd = row_rstd(ss, row0 + ai * HALF + m * 16, fq);
; #pragma unroll
;                 for (int bj = 0; bj < 2; ++bj) { acc[ai][bj][m][0] *= rstd; acc[ai][bj][m][1] *= rstd; } }
.LBB0_755:
	s_waitcnt vmcnt(14)
	v_add_f32_e32 v174, v174, v175
	v_add_f32_e32 v176, v176, v177
	v_add_f32_e32 v178, v178, v179
	v_add_f32_e32 v180, v180, v181
	v_add_f32_e32 v174, v174, v176
	v_add_f32_e32 v178, v178, v180
	v_add_f32_e32 v130, v174, v178
	s_waitcnt vmcnt(12)
	v_add_f32_e32 v182, v182, v183
	v_add_f32_e32 v184, v184, v185
	v_add_f32_e32 v186, v186, v187
	v_add_f32_e32 v188, v188, v189
	v_add_f32_e32 v182, v182, v184
	v_add_f32_e32 v186, v186, v188
	v_add_f32_e32 v132, v182, v186
	s_waitcnt vmcnt(10)
	v_add_f32_e32 v190, v190, v191
	v_add_f32_e32 v192, v192, v193
	v_add_f32_e32 v194, v194, v195
	v_add_f32_e32 v196, v196, v197
	v_add_f32_e32 v190, v190, v192
	v_add_f32_e32 v194, v194, v196
	v_add_f32_e32 v134, v190, v194
	s_waitcnt vmcnt(8)
	v_add_f32_e32 v198, v198, v199
	v_add_f32_e32 v200, v200, v201
	v_add_f32_e32 v202, v202, v203
	v_add_f32_e32 v204, v204, v205
	v_add_f32_e32 v198, v198, v200
	v_add_f32_e32 v202, v202, v204
	v_add_f32_e32 v136, v198, v202
	s_waitcnt vmcnt(6)
	v_add_f32_e32 v206, v206, v207
	v_add_f32_e32 v208, v208, v209
	v_add_f32_e32 v210, v210, v211
	v_add_f32_e32 v212, v212, v213
	v_add_f32_e32 v206, v206, v208
	v_add_f32_e32 v210, v210, v212
	v_add_f32_e32 v138, v206, v210
	s_waitcnt vmcnt(4)
	v_add_f32_e32 v214, v214, v215
	v_add_f32_e32 v216, v216, v217
	v_add_f32_e32 v218, v218, v219
	v_add_f32_e32 v220, v220, v221
	v_add_f32_e32 v214, v214, v216
	v_add_f32_e32 v218, v218, v220
	v_add_f32_e32 v140, v214, v218
	s_waitcnt vmcnt(2)
	v_add_f32_e32 v222, v222, v223
	v_add_f32_e32 v224, v224, v225
	v_add_f32_e32 v226, v226, v227
	v_add_f32_e32 v228, v228, v229
	v_add_f32_e32 v222, v222, v224
	v_add_f32_e32 v226, v226, v228
	v_add_f32_e32 v142, v222, v226
	s_waitcnt vmcnt(0)
	v_add_f32_e32 v230, v230, v231
	v_add_f32_e32 v232, v232, v233
	v_add_f32_e32 v234, v234, v235
	v_add_f32_e32 v236, v236, v237
	v_add_f32_e32 v230, v230, v232
	v_add_f32_e32 v234, v234, v236
	v_add_f32_e32 v144, v230, v234
	ds_bpermute_b32 v174, v238, v130
	ds_bpermute_b32 v175, v238, v132
	ds_bpermute_b32 v176, v238, v134
	ds_bpermute_b32 v177, v238, v136
	ds_bpermute_b32 v178, v238, v138
	ds_bpermute_b32 v179, v238, v140
	ds_bpermute_b32 v180, v238, v142
	ds_bpermute_b32 v181, v238, v144
	s_waitcnt lgkmcnt(0)
	v_add_f32_e32 v130, v130, v174
	v_add_f32_e32 v132, v132, v175
	v_add_f32_e32 v134, v134, v176
	v_add_f32_e32 v136, v136, v177
	v_add_f32_e32 v138, v138, v178
	v_add_f32_e32 v140, v140, v179
	v_add_f32_e32 v142, v142, v180
	v_add_f32_e32 v144, v144, v181
	ds_bpermute_b32 v174, v239, v130
	ds_bpermute_b32 v175, v239, v132
	ds_bpermute_b32 v176, v239, v134
	ds_bpermute_b32 v177, v239, v136
	ds_bpermute_b32 v178, v239, v138
	ds_bpermute_b32 v179, v239, v140
	ds_bpermute_b32 v180, v239, v142
	ds_bpermute_b32 v181, v239, v144
	s_waitcnt lgkmcnt(0)
	v_add_f32_e32 v130, v130, v174
	v_add_f32_e32 v132, v132, v175
	v_add_f32_e32 v134, v134, v176
	v_add_f32_e32 v136, v136, v177
	v_add_f32_e32 v138, v138, v178
	v_add_f32_e32 v140, v140, v179
	v_add_f32_e32 v142, v142, v180
	v_add_f32_e32 v144, v144, v181
	v_fmamk_f32 v130, v130, 0x3a000000, v243
	v_fmamk_f32 v132, v132, 0x3a000000, v243
	v_fmamk_f32 v134, v134, 0x3a000000, v243
	v_fmamk_f32 v136, v136, 0x3a000000, v243
	v_fmamk_f32 v138, v138, 0x3a000000, v243
	v_fmamk_f32 v140, v140, 0x3a000000, v243
	v_fmamk_f32 v142, v142, 0x3a000000, v243
	v_fmamk_f32 v144, v144, 0x3a000000, v243
	v_rsq_f32_e32 v130, v130
	v_rsq_f32_e32 v132, v132
	v_rsq_f32_e32 v134, v134
	v_rsq_f32_e32 v136, v136
	v_rsq_f32_e32 v138, v138
	v_rsq_f32_e32 v140, v140
	v_rsq_f32_e32 v142, v142
	v_rsq_f32_e32 v144, v144
	s_nop 0
	v_pk_mul_f32 v[126:127], v[126:127], v[130:131] op_sel_hi:[1,0]
	v_pk_mul_f32 v[128:129], v[128:129], v[130:131] op_sel_hi:[1,0]
	v_pk_mul_f32 v[62:63], v[62:63], v[130:131] op_sel_hi:[1,0]
	v_pk_mul_f32 v[64:65], v[64:65], v[130:131] op_sel_hi:[1,0]
	v_pk_mul_f32 v[122:123], v[122:123], v[130:131] op_sel_hi:[1,0]
	v_pk_mul_f32 v[124:125], v[124:125], v[130:131] op_sel_hi:[1,0]
	v_pk_mul_f32 v[54:55], v[54:55], v[130:131] op_sel_hi:[1,0]
	v_pk_mul_f32 v[56:57], v[56:57], v[130:131] op_sel_hi:[1,0]
	v_pk_mul_f32 v[118:119], v[118:119], v[132:133] op_sel_hi:[1,0]
	v_pk_mul_f32 v[120:121], v[120:121], v[132:133] op_sel_hi:[1,0]
	v_pk_mul_f32 v[58:59], v[58:59], v[132:133] op_sel_hi:[1,0]
	v_pk_mul_f32 v[60:61], v[60:61], v[132:133] op_sel_hi:[1,0]
	v_pk_mul_f32 v[114:115], v[114:115], v[132:133] op_sel_hi:[1,0]
	v_pk_mul_f32 v[116:117], v[116:117], v[132:133] op_sel_hi:[1,0]
	v_pk_mul_f32 v[50:51], v[50:51], v[132:133] op_sel_hi:[1,0]
	v_pk_mul_f32 v[52:53], v[52:53], v[132:133] op_sel_hi:[1,0]
	v_pk_mul_f32 v[110:111], v[110:111], v[134:135] op_sel_hi:[1,0]
	v_pk_mul_f32 v[112:113], v[112:113], v[134:135] op_sel_hi:[1,0]
	v_pk_mul_f32 v[46:47], v[46:47], v[134:135] op_sel_hi:[1,0]
	v_pk_mul_f32 v[48:49], v[48:49], v[134:135] op_sel_hi:[1,0]
	v_pk_mul_f32 v[102:103], v[102:103], v[134:135] op_sel_hi:[1,0]
	v_pk_mul_f32 v[104:105], v[104:105], v[134:135] op_sel_hi:[1,0]
	v_pk_mul_f32 v[38:39], v[38:39], v[134:135] op_sel_hi:[1,0]
	v_pk_mul_f32 v[40:41], v[40:41], v[134:135] op_sel_hi:[1,0]
	v_pk_mul_f32 v[106:107], v[106:107], v[136:137] op_sel_hi:[1,0]
	v_pk_mul_f32 v[108:109], v[108:109], v[136:137] op_sel_hi:[1,0]
	v_pk_mul_f32 v[42:43], v[42:43], v[136:137] op_sel_hi:[1,0]
	v_pk_mul_f32 v[44:45], v[44:45], v[136:137] op_sel_hi:[1,0]
	v_pk_mul_f32 v[98:99], v[98:99], v[136:137] op_sel_hi:[1,0]
	v_pk_mul_f32 v[100:101], v[100:101], v[136:137] op_sel_hi:[1,0]
	v_pk_mul_f32 v[34:35], v[34:35], v[136:137] op_sel_hi:[1,0]
	v_pk_mul_f32 v[36:37], v[36:37], v[136:137] op_sel_hi:[1,0]
;     __device__ __forceinline__ void operator()(f32x4 (&acc)[2][2][4][2], const Unit& u, int wr, int wc, int fr, int fq) const {
;     ...
;             for (int m = 0; m < 4; ++m) { const float rstd = row_rstd(ss, row0 + ai * HALF + m * 16, fq);
; #pragma unroll
;                 for (int bj = 0; bj < 2; ++bj) { acc[ai][bj][m][0] *= rstd; acc[ai][bj][m][1] *= rstd; } }
; #pragma unroll
;         for (int n = 0; n < 2; ++n) {
;             const int j4 = u.pn * 128 + wc * 32 + 8 * fq + 4 * n;
;             f32x4 kc[2][3], bc[2];
; #pragma unroll
;             for (int bj = 0; bj < 2; ++bj) { bc[bj] = *(const f32x4*)(cb + bj * FF + j4);
; #pragma unroll
;                 for (int w = 0; w < 3; ++w) kc[bj][w] = *(const f32x4*)(ck + w * NUP + bj * FF + j4); }
; #pragma unroll
;             for (int ai = 0; ai < 2; ++ai) {
;                 const int grp = u.pm * 4 + ai * 2 + wr;
; #pragma unroll
;                 for (int m = 0; m < 4; ++m) {
;                     f32x4 cv[2];
; #pragma unroll
;                     for (int bj = 0; bj < 2; ++bj) {
;                         const f32x4 cur = acc[ai][bj][m][n], lo = acc[ai][bj][m > 0 ? m - 1 : 0][n], hi = acc[ai][bj][m < 3 ? m + 1 : 3][n];
;                         f32x4 pv, nv;
; #pragma unroll
;                         for (int idx = 0; idx < 4; ++idx) {
;                             const float y = (fr == 15) ? lo[idx] : cur[idx], z = (fr == 0) ? hi[idx] : cur[idx];
;                             pv[idx] = __int_as_float(__builtin_amdgcn_update_dpp(0, __float_as_int(y), 0x121, 0xf, 0xf, false));
;                             nv[idx] = __int_as_float(__builtin_amdgcn_update_dpp(0, __float_as_int(z), 0x12f, 0xf, 0xf, false));
;                         }
;                         cv[bj] = kc[bj][0] * pv + kc[bj][1] * cur + kc[bj][2] * nv + bc[bj];
	v_pk_mul_f32 v[94:95], v[94:95], v[138:139] op_sel_hi:[1,0]
	v_pk_mul_f32 v[96:97], v[96:97], v[138:139] op_sel_hi:[1,0]
	v_pk_mul_f32 v[30:31], v[30:31], v[138:139] op_sel_hi:[1,0]
	v_pk_mul_f32 v[32:33], v[32:33], v[138:139] op_sel_hi:[1,0]
	v_pk_mul_f32 v[86:87], v[86:87], v[138:139] op_sel_hi:[1,0]
	v_pk_mul_f32 v[88:89], v[88:89], v[138:139] op_sel_hi:[1,0]
	v_pk_mul_f32 v[22:23], v[22:23], v[138:139] op_sel_hi:[1,0]
	v_pk_mul_f32 v[24:25], v[24:25], v[138:139] op_sel_hi:[1,0]
	v_pk_mul_f32 v[90:91], v[90:91], v[140:141] op_sel_hi:[1,0]
	v_pk_mul_f32 v[92:93], v[92:93], v[140:141] op_sel_hi:[1,0]
	v_pk_mul_f32 v[26:27], v[26:27], v[140:141] op_sel_hi:[1,0]
	v_pk_mul_f32 v[28:29], v[28:29], v[140:141] op_sel_hi:[1,0]
	v_pk_mul_f32 v[82:83], v[82:83], v[140:141] op_sel_hi:[1,0]
	v_pk_mul_f32 v[84:85], v[84:85], v[140:141] op_sel_hi:[1,0]
	v_pk_mul_f32 v[18:19], v[18:19], v[140:141] op_sel_hi:[1,0]
	v_pk_mul_f32 v[20:21], v[20:21], v[140:141] op_sel_hi:[1,0]
	v_pk_mul_f32 v[78:79], v[78:79], v[142:143] op_sel_hi:[1,0]
	v_pk_mul_f32 v[80:81], v[80:81], v[142:143] op_sel_hi:[1,0]
	v_pk_mul_f32 v[14:15], v[14:15], v[142:143] op_sel_hi:[1,0]
	v_pk_mul_f32 v[16:17], v[16:17], v[142:143] op_sel_hi:[1,0]
	v_pk_mul_f32 v[70:71], v[70:71], v[142:143] op_sel_hi:[1,0]
	v_pk_mul_f32 v[72:73], v[72:73], v[142:143] op_sel_hi:[1,0]
	v_pk_mul_f32 v[6:7], v[6:7], v[142:143] op_sel_hi:[1,0]
	v_pk_mul_f32 v[8:9], v[8:9], v[142:143] op_sel_hi:[1,0]
	v_pk_mul_f32 v[74:75], v[74:75], v[144:145] op_sel_hi:[1,0]
	v_pk_mul_f32 v[76:77], v[76:77], v[144:145] op_sel_hi:[1,0]
	v_pk_mul_f32 v[10:11], v[10:11], v[144:145] op_sel_hi:[1,0]
	v_pk_mul_f32 v[12:13], v[12:13], v[144:145] op_sel_hi:[1,0]
	v_pk_mul_f32 v[66:67], v[66:67], v[144:145] op_sel_hi:[1,0]
	v_pk_mul_f32 v[68:69], v[68:69], v[144:145] op_sel_hi:[1,0]
	v_pk_mul_f32 v[2:3], v[2:3], v[144:145] op_sel_hi:[1,0]
	v_pk_mul_f32 v[4:5], v[4:5], v[144:145] op_sel_hi:[1,0]
	v_and_b32_e32 v131, 64, v241
	v_xor_b32_e32 v130, 16, v241
	v_add_u32_e32 v131, 64, v131
	v_lshl_add_u32 v176, s12, 8, v247
	v_cmp_lt_i32_e32 vcc, v130, v131
	v_xor_b32_e32 v132, 32, v241
	v_ashrrev_i32_e32 v177, 31, v176
	v_cndmask_b32_e32 v130, v241, v130, vcc
	v_cmp_lt_i32_e32 vcc, v132, v131
	v_lshlrev_b32_e32 v130, 2, v130
	v_or_b32_e32 v194, 16, v176
	v_cndmask_b32_e32 v131, v241, v132, vcc
	v_lshlrev_b64 v[132:133], 7, v[176:177]
	v_lshl_add_u64 v[136:137], v[152:153], 0, v[132:133]
	s_nop 0
	v_lshlrev_b32_e32 v131, 2, v131
	v_ashrrev_i32_e32 v195, 31, v194
	v_or_b32_e32 v192, 32, v176
	v_ashrrev_i32_e32 v193, 31, v192
	v_or_b32_e32 v160, 48, v176
	v_ashrrev_i32_e32 v161, 31, v160
	v_add_u32_e32 v158, 0x80, v176
	v_ashrrev_i32_e32 v159, 31, v158
	v_add_u32_e32 v186, 0x90, v176
	v_ashrrev_i32_e32 v187, 31, v186
	v_add_u32_e32 v184, 0xa0, v176
	v_ashrrev_i32_e32 v185, 31, v184
	v_add_u32_e32 v174, 0xb0, v176
	v_ashrrev_i32_e32 v175, 31, v174
	v_lshl_or_b32 v178, s16, 7, v250
	v_ashrrev_i32_e32 v179, 31, v178
	s_mov_b32 s13, 0xa000
	v_mov_b32_e32 v226, v1
	v_mov_b32_e32 v227, v1
	v_mov_b32_e32 v228, v1
	v_mov_b32_e32 v229, v1
	v_mov_b32_e32 v230, v1
	v_mov_b32_e32 v231, v1
	v_mov_b32_e32 v234, v1
	v_mov_b32_e32 v235, v1
	v_mov_b32_e32 v238, v1
	v_mov_b32_e32 v239, v1
	s_nop 0
	s_nop 0
	s_waitcnt lgkmcnt(0)
	s_waitcnt lgkmcnt(0)
	v_mov_b32_e32 v180, 1.0
	s_nop 0
	v_pk_mul_f32 v[208:209], v[122:123], v[180:181] op_sel_hi:[1,0]
	v_lshlrev_b64 v[122:123], 7, v[194:195]
	v_pk_mul_f32 v[220:221], v[126:127], v[180:181] op_sel_hi:[1,0]
	v_lshl_add_u64 v[126:127], v[152:153], 0, v[122:123]
	v_pk_mul_f32 v[212:213], v[128:129], v[180:181] op_sel_hi:[1,0]
	v_pk_mul_f32 v[198:199], v[124:125], v[180:181] op_sel_hi:[1,0]
	s_nop 0
	v_mov_b32_dpp v228, v220 row_ror:1 row_mask:0xf bank_mask:0xf
	v_mov_b32_dpp v229, v221 row_ror:1 row_mask:0xf bank_mask:0xf
	v_mov_b32_dpp v230, v212 row_ror:1 row_mask:0xf bank_mask:0xf
	v_mov_b32_dpp v231, v213 row_ror:1 row_mask:0xf bank_mask:0xf
	v_mov_b32_dpp v234, v208 row_ror:1 row_mask:0xf bank_mask:0xf
	v_mov_b32_dpp v235, v209 row_ror:1 row_mask:0xf bank_mask:0xf
	v_mov_b32_dpp v238, v198 row_ror:1 row_mask:0xf bank_mask:0xf
	v_mov_b32_dpp v239, v199 row_ror:1 row_mask:0xf bank_mask:0xf
	s_nop 0
	s_nop 0
	s_waitcnt lgkmcnt(0)
	s_waitcnt lgkmcnt(0)
; __device__ __forceinline__ unsigned cvt_pk_bf16(float lo, float hi) { unsigned r; asm volatile("v_cvt_pk_bf16_f32 %0, %1, %2" : "=v"(r) : "v"(lo), "v"(hi)); return r; }
; __device__ __forceinline__ float sigmoid_f(float x) { return fast_rcp(1.0f + fast_exp2(-1.4426950409f * x)); }
;     __device__ __forceinline__ void operator()(f32x4 (&acc)[2][2][4][2], const Unit& u, int wr, int wc, int fr, int fq) const {
;     ...
;         for (int n = 0; n < 2; ++n) {
;             const int j4 = u.pn * 128 + wc * 32 + 8 * fq + 4 * n;
;             f32x4 kc[2][3], bc[2];
; #pragma unroll
;             for (int bj = 0; bj < 2; ++bj) { bc[bj] = *(const f32x4*)(cb + bj * FF + j4);
; #pragma unroll
;                 for (int w = 0; w < 3; ++w) kc[bj][w] = *(const f32x4*)(ck + w * NUP + bj * FF + j4); }
; #pragma unroll
;             for (int ai = 0; ai < 2; ++ai) {
;                 const int grp = u.pm * 4 + ai * 2 + wr;
; #pragma unroll
;                 for (int m = 0; m < 4; ++m) {
;                     f32x4 cv[2];
; #pragma unroll
;                     for (int bj = 0; bj < 2; ++bj) {
;                         const f32x4 cur = acc[ai][bj][m][n], lo = acc[ai][bj][m > 0 ? m - 1 : 0][n], hi = acc[ai][bj][m < 3 ? m + 1 : 3][n];
;                         f32x4 pv, nv;
; #pragma unroll
;                         for (int idx = 0; idx < 4; ++idx) {
;                             const float y = (fr == 15) ? lo[idx] : cur[idx], z = (fr == 0) ? hi[idx] : cur[idx];
;                             pv[idx] = __int_as_float(__builtin_amdgcn_update_dpp(0, __float_as_int(y), 0x121, 0xf, 0xf, false));
;                             nv[idx] = __int_as_float(__builtin_amdgcn_update_dpp(0, __float_as_int(z), 0x12f, 0xf, 0xf, false));
;                         }
;                         cv[bj] = kc[bj][0] * pv + kc[bj][1] * cur + kc[bj][2] * nv + bc[bj];
;                     }
;                     const int row = row0 + ai * HALF + m * 16;
;                     const bool edge = (m == 0 && fr == 0) || (m == 3 && fr == 15);
;                     if (!edge) { const f32x4 gt = cv[0], vl = cv[1];
;                         u32x2 w; w.x = cvt_pk_bf16(gt[0] * sigmoid_f(gt[0]) * vl[0], gt[1] * sigmoid_f(gt[1]) * vl[1]); w.y = cvt_pk_bf16(gt[2] * sigmoid_f(gt[2]) * vl[2], gt[3] * sigmoid_f(gt[3]) * vl[3]);
;                         *(u32x2*)(ACT + (size_t)row * FF + j4) = w; }
	v_mov_b32_e32 v182, 1.0
	s_nop 0
	v_pk_mul_f32 v[190:191], v[114:115], v[182:183] op_sel_hi:[1,0]
	v_lshlrev_b64 v[114:115], 7, v[192:193]
	v_pk_mul_f32 v[200:201], v[118:119], v[182:183] op_sel_hi:[1,0]
	v_lshl_add_u64 v[118:119], v[152:153], 0, v[114:115]
	v_pk_mul_f32 v[196:197], v[120:121], v[182:183] op_sel_hi:[1,0]
	v_pk_mul_f32 v[188:189], v[116:117], v[182:183] op_sel_hi:[1,0]
	s_nop 0
	v_cndmask_b32_e64 v224, v220, v200, s[42:43]
	v_cndmask_b32_e64 v225, v212, v196, s[42:43]
	v_cndmask_b32_e64 v232, v213, v197, s[42:43]
	v_mov_b32_dpp v226, v224 row_ror:15 row_mask:0xf bank_mask:0xf
	v_cndmask_b32_e64 v224, v221, v201, s[42:43]
	v_cndmask_b32_e64 v233, v208, v190, s[42:43]
	v_cndmask_b32_e64 v236, v209, v191, s[42:43]
	v_mov_b32_dpp v227, v224 row_ror:15 row_mask:0xf bank_mask:0xf
	v_mov_b32_e32 v224, v1
	v_cndmask_b32_e64 v237, v198, v188, s[42:43]
	v_cndmask_b32_e64 v242, v199, v189, s[42:43]
	v_mov_b32_dpp v224, v225 row_ror:15 row_mask:0xf bank_mask:0xf
	v_mov_b32_e32 v225, v1
	v_mov_b32_dpp v225, v232 row_ror:15 row_mask:0xf bank_mask:0xf
	v_mov_b32_e32 v232, v1
	v_mov_b32_dpp v232, v233 row_ror:15 row_mask:0xf bank_mask:0xf
	v_mov_b32_e32 v233, v1
	s_waitcnt lgkmcnt(0)
	v_lshlrev_b64 v[114:115], 7, v[160:161]
	v_lshl_add_u64 v[118:119], v[152:153], 0, v[114:115]
	s_nop 0
	v_mov_b32_dpp v233, v236 row_ror:15 row_mask:0xf bank_mask:0xf
	v_mov_b32_e32 v236, v1
	v_mov_b32_dpp v236, v237 row_ror:15 row_mask:0xf bank_mask:0xf
	v_mov_b32_e32 v237, v1
	v_mov_b32_dpp v237, v242 row_ror:15 row_mask:0xf bank_mask:0xf
	s_waitcnt lgkmcnt(0)
	v_lshlrev_b64 v[114:115], 7, v[158:159]
	v_lshl_add_u64 v[118:119], v[152:153], 0, v[114:115]
	s_nop 0
	s_nop 0
	s_nop 0
	s_waitcnt lgkmcnt(0)
	v_lshlrev_b64 v[114:115], 7, v[186:187]
	v_lshl_add_u64 v[118:119], v[152:153], 0, v[114:115]
	s_nop 0
	s_nop 0
	s_nop 0
	s_waitcnt lgkmcnt(0)
	v_lshlrev_b64 v[114:115], 7, v[184:185]
	v_lshl_add_u64 v[118:119], v[152:153], 0, v[114:115]
	s_nop 0
	s_nop 0
	s_nop 0
	s_waitcnt lgkmcnt(0)
	v_lshlrev_b64 v[114:115], 7, v[174:175]
	v_lshl_add_u64 v[118:119], v[152:153], 0, v[114:115]
	s_nop 0
	s_nop 0
	s_nop 0
	s_waitcnt lgkmcnt(0)
	v_lshlrev_b64 v[114:115], 2, v[178:179]
	v_lshl_add_u64 v[204:205], s[18:19], 0, v[114:115]
	v_add_co_u32_e32 v206, vcc, s13, v204
	s_mov_b32 s13, 0x15000
	s_nop 0
	v_addc_co_u32_e32 v207, vcc, 0, v205, vcc
	v_add_co_u32_e32 v210, vcc, s13, v204
	v_lshl_add_u64 v[202:203], s[20:21], 0, v[114:115]
	s_nop 0
	v_addc_co_u32_e32 v211, vcc, 0, v205, vcc
	v_add_co_u32_e32 v214, vcc, s33, v202
	s_mov_b32 s13, 0x1a000
	s_nop 0
	v_addc_co_u32_e32 v215, vcc, 0, v203, vcc
	v_add_co_u32_e32 v216, vcc, s33, v204
	s_nop 0
	v_addc_co_u32_e32 v217, vcc, 0, v205, vcc
	v_add_co_u32_e32 v218, vcc, s65, v204
	global_load_dwordx4 v[114:117], v[202:203], off
	global_load_dwordx4 v[122:125], v[204:205], off
	v_addc_co_u32_e32 v219, vcc, 0, v205, vcc
	v_add_co_u32_e32 v222, vcc, s13, v204
	global_load_dwordx4 v[126:129], v[206:207], off offset:3072
	global_load_dwordx4 v[118:121], v[210:211], off offset:2048
	v_addc_co_u32_e32 v223, vcc, 0, v205, vcc
	global_load_dwordx4 v[130:133], v[214:215], off offset:1536
	global_load_dwordx4 v[134:137], v[216:217], off offset:1536
	global_load_dwordx4 v[138:141], v[218:219], off offset:512
	global_load_dwordx4 v[142:145], v[222:223], off offset:3584
	s_and_saveexec_b64 s[16:17], s[44:45]
	s_cbranch_execz .LBB0_757
	s_waitcnt vmcnt(6)
	v_pk_mul_f32 v[228:229], v[122:123], v[228:229]
	v_pk_mul_f32 v[230:231], v[124:125], v[230:231]
	s_waitcnt vmcnt(5)
	v_pk_fma_f32 v[228:229], v[220:221], v[126:127], v[228:229]
	v_pk_fma_f32 v[230:231], v[212:213], v[128:129], v[230:231]
	s_waitcnt vmcnt(4)
	v_pk_fma_f32 v[226:227], v[118:119], v[226:227], v[228:229]
	v_pk_fma_f32 v[224:225], v[120:121], v[224:225], v[230:231]
	v_pk_add_f32 v[226:227], v[114:115], v[226:227]
	v_pk_add_f32 v[224:225], v[116:117], v[224:225]
	v_mul_f32_e32 v228, 0xbfb8aa3b, v226
	v_mul_f32_e32 v229, 0xbfb8aa3b, v227
	v_exp_f32_e32 v228, v228
	v_exp_f32_e32 v229, v229
	s_waitcnt vmcnt(2)
	v_pk_mul_f32 v[238:239], v[136:137], v[238:239]
	v_pk_mul_f32 v[234:235], v[134:135], v[234:235]
	v_add_f32_e32 v228, 1.0, v228
	v_add_f32_e32 v229, 1.0, v229
	v_rcp_f32_e32 v228, v228
	v_rcp_f32_e32 v229, v229
	s_waitcnt vmcnt(1)
	v_pk_fma_f32 v[238:239], v[198:199], v[140:141], v[238:239]
	v_pk_fma_f32 v[234:235], v[208:209], v[138:139], v[234:235]
	v_mul_f32_e32 v226, v226, v228
	v_mul_f32_e32 v227, v227, v229
	v_mul_f32_e32 v228, 0xbfb8aa3b, v224
	v_mul_f32_e32 v229, 0xbfb8aa3b, v225
	v_exp_f32_e32 v228, v228
	v_exp_f32_e32 v229, v229
	s_waitcnt vmcnt(0)
	v_pk_fma_f32 v[236:237], v[144:145], v[236:237], v[238:239]
	v_pk_fma_f32 v[232:233], v[142:143], v[232:233], v[234:235]
	v_add_f32_e32 v228, 1.0, v228
	v_add_f32_e32 v229, 1.0, v229
	v_rcp_f32_e32 v228, v228
	v_rcp_f32_e32 v229, v229
	v_pk_add_f32 v[232:233], v[130:131], v[232:233]
	v_pk_add_f32 v[234:235], v[132:133], v[236:237]
	v_mul_f32_e32 v224, v224, v228
	v_mul_f32_e32 v225, v225, v229
	v_mul_f32_e32 v226, v226, v232
	v_mul_f32_e32 v227, v227, v233
	v_mul_f32_e32 v224, v224, v234
	v_mul_f32_e32 v225, v225, v235
	v_cvt_pk_bf16_f32 v226, v226, v227
	v_cvt_pk_bf16_f32 v227, v224, v225
	v_mov_b64_e32 v[224:225], s[30:31]
	v_mad_i64_i32 v[224:225], s[34:35], v176, s7, v[224:225]
	v_lshl_add_u64 v[224:225], v[178:179], 1, v[224:225]
	global_store_dwordx2 v[224:225], v[226:227], off

; __device__ __forceinline__ unsigned cvt_pk_bf16(float lo, float hi) { unsigned r; asm volatile("v_cvt_pk_bf16_f32 %0, %1, %2" : "=v"(r) : "v"(lo), "v"(hi)); return r; }
; __device__ __forceinline__ float sigmoid_f(float x) { return fast_rcp(1.0f + fast_exp2(-1.4426950409f * x)); }
;     __device__ __forceinline__ void operator()(f32x4 (&acc)[2][2][4][2], const Unit& u, int wr, int wc, int fr, int fq) const {
;     ...
;             for (int ai = 0; ai < 2; ++ai) {
;                 const int grp = u.pm * 4 + ai * 2 + wr;
; #pragma unroll
;                 for (int m = 0; m < 4; ++m) {
;                     f32x4 cv[2];
; #pragma unroll
;                     for (int bj = 0; bj < 2; ++bj) {
;                         const f32x4 cur = acc[ai][bj][m][n], lo = acc[ai][bj][m > 0 ? m - 1 : 0][n], hi = acc[ai][bj][m < 3 ? m + 1 : 3][n];
;                         f32x4 pv, nv;
; #pragma unroll
;                         for (int idx = 0; idx < 4; ++idx) {
;                             const float y = (fr == 15) ? lo[idx] : cur[idx], z = (fr == 0) ? hi[idx] : cur[idx];
;                             pv[idx] = __int_as_float(__builtin_amdgcn_update_dpp(0, __float_as_int(y), 0x121, 0xf, 0xf, false));
;                             nv[idx] = __int_as_float(__builtin_amdgcn_update_dpp(0, __float_as_int(z), 0x12f, 0xf, 0xf, false));
;                         }
;                         cv[bj] = kc[bj][0] * pv + kc[bj][1] * cur + kc[bj][2] * nv + bc[bj];
;                     }
;                     const int row = row0 + ai * HALF + m * 16;
;                     const bool edge = (m == 0 && fr == 0) || (m == 3 && fr == 15);
;                     if (!edge) { const f32x4 gt = cv[0], vl = cv[1];
;                         u32x2 w; w.x = cvt_pk_bf16(gt[0] * sigmoid_f(gt[0]) * vl[0], gt[1] * sigmoid_f(gt[1]) * vl[1]); w.y = cvt_pk_bf16(gt[2] * sigmoid_f(gt[2]) * vl[2], gt[3] * sigmoid_f(gt[3]) * vl[3]);
;                         *(u32x2*)(ACT + (size_t)row * FF + j4) = w; }
.LBB0_759:
	s_or_b64 exec, exec, s[12:13]
	v_mov_b32_e32 v228, 1.0
	v_mov_b32_e32 v230, 1.0
	v_pk_mul_f32 v[238:239], v[110:111], v[228:229] op_sel_hi:[1,0]
	v_pk_mul_f32 v[234:235], v[102:103], v[228:229] op_sel_hi:[1,0]
	v_pk_mul_f32 v[236:237], v[112:113], v[228:229] op_sel_hi:[1,0]
	v_pk_mul_f32 v[110:111], v[108:109], v[230:231] op_sel_hi:[1,0]
	v_pk_mul_f32 v[102:103], v[100:101], v[230:231] op_sel_hi:[1,0]
	v_pk_mul_f32 v[108:109], v[98:99], v[230:231] op_sel_hi:[1,0]
	v_cndmask_b32_e64 v99, v200, v220, s[38:39]
	v_cndmask_b32_e64 v101, v200, v238, s[42:43]
	v_mov_b32_e32 v98, v1
	v_mov_b32_e32 v100, v1
	v_pk_mul_f32 v[232:233], v[104:105], v[228:229] op_sel_hi:[1,0]
	v_mov_b32_dpp v98, v99 row_ror:1 row_mask:0xf bank_mask:0xf
	v_mov_b32_dpp v100, v101 row_ror:15 row_mask:0xf bank_mask:0xf
	v_cndmask_b32_e64 v101, v201, v221, s[38:39]
	v_mov_b32_e32 v99, v1
	v_cndmask_b32_e64 v104, v201, v239, s[42:43]
	v_pk_mul_f32 v[112:113], v[106:107], v[230:231] op_sel_hi:[1,0]
	v_mov_b32_dpp v99, v101 row_ror:1 row_mask:0xf bank_mask:0xf
	v_mov_b32_e32 v101, v1
	v_cndmask_b32_e64 v105, v196, v212, s[38:39]
	v_cndmask_b32_e64 v107, v196, v236, s[42:43]
	v_mov_b32_dpp v101, v104 row_ror:15 row_mask:0xf bank_mask:0xf
	v_mov_b32_e32 v104, v1
	v_mov_b32_e32 v106, v1
	v_cndmask_b32_e64 v193, v197, v237, s[42:43]
	v_mov_b32_dpp v104, v105 row_ror:1 row_mask:0xf bank_mask:0xf
	v_mov_b32_dpp v106, v107 row_ror:15 row_mask:0xf bank_mask:0xf
	v_cndmask_b32_e64 v107, v197, v213, s[38:39]
	v_mov_b32_e32 v105, v1
	s_waitcnt vmcnt(6)
	v_pk_mul_f32 v[98:99], v[122:123], v[98:99]
	v_cndmask_b32_e64 v195, v190, v234, s[42:43]
	v_mov_b32_dpp v105, v107 row_ror:1 row_mask:0xf bank_mask:0xf
	v_mov_b32_e32 v107, v1
	s_waitcnt vmcnt(5)
	v_pk_fma_f32 v[98:99], v[200:201], v[126:127], v[98:99]
	v_mov_b32_e32 v212, v1
	v_mov_b32_dpp v107, v193 row_ror:15 row_mask:0xf bank_mask:0xf
	v_cndmask_b32_e64 v193, v190, v208, s[38:39]
	v_mov_b32_e32 v208, v1
	s_waitcnt vmcnt(4)
	v_pk_fma_f32 v[98:99], v[118:119], v[100:101], v[98:99]
	v_mov_b32_dpp v212, v195 row_ror:15 row_mask:0xf bank_mask:0xf
	v_mov_b32_dpp v208, v193 row_ror:1 row_mask:0xf bank_mask:0xf
	v_cndmask_b32_e64 v193, v191, v209, s[38:39]
	v_mov_b32_e32 v209, v1
	v_cndmask_b32_e64 v195, v191, v235, s[42:43]
	v_mov_b32_e32 v213, v1
	v_mov_b32_dpp v209, v193 row_ror:1 row_mask:0xf bank_mask:0xf
	v_cndmask_b32_e64 v193, v188, v198, s[38:39]
	v_mov_b32_e32 v198, v1
	v_pk_add_f32 v[98:99], v[114:115], v[98:99]
	v_mov_b32_dpp v213, v195 row_ror:15 row_mask:0xf bank_mask:0xf
	v_cndmask_b32_e64 v195, v188, v232, s[42:43]
	v_mov_b32_dpp v198, v193 row_ror:1 row_mask:0xf bank_mask:0xf
	v_mov_b32_e32 v220, v1
	v_cndmask_b32_e64 v193, v189, v199, s[38:39]
	v_mov_b32_e32 v199, v1
	v_mul_f32_e32 v100, 0xbfb8aa3b, v98
	v_mov_b32_dpp v220, v195 row_ror:15 row_mask:0xf bank_mask:0xf
	v_cndmask_b32_e64 v195, v189, v233, s[42:43]
	v_mov_b32_dpp v199, v193 row_ror:1 row_mask:0xf bank_mask:0xf
	v_mov_b32_e32 v221, v1
	v_exp_f32_e32 v193, v100
	v_mul_f32_e32 v100, 0xbfb8aa3b, v99
	v_mov_b32_dpp v221, v195 row_ror:15 row_mask:0xf bank_mask:0xf
	v_exp_f32_e32 v195, v100
	v_pk_mul_f32 v[104:105], v[124:125], v[104:105]
	s_waitcnt vmcnt(2)
	v_pk_mul_f32 v[208:209], v[134:135], v[208:209]
	v_pk_fma_f32 v[104:105], v[196:197], v[128:129], v[104:105]
	s_waitcnt vmcnt(1)
	v_pk_fma_f32 v[208:209], v[190:191], v[138:139], v[208:209]
	v_pk_fma_f32 v[100:101], v[120:121], v[106:107], v[104:105]
	v_add_f32_e32 v104, 1.0, v193
	v_add_f32_e32 v105, 1.0, v195
	v_rcp_f32_e32 v104, v104
	v_rcp_f32_e32 v105, v105
	v_pk_add_f32 v[100:101], v[116:117], v[100:101]
	v_pk_mul_f32 v[198:199], v[136:137], v[198:199]
	v_mul_f32_e32 v98, v98, v104
	v_mul_f32_e32 v99, v99, v105
	v_mul_f32_e32 v104, 0xbfb8aa3b, v100
	v_mul_f32_e32 v105, 0xbfb8aa3b, v101
	v_exp_f32_e32 v104, v104
	v_exp_f32_e32 v105, v105
	s_waitcnt vmcnt(0)
	v_pk_fma_f32 v[208:209], v[142:143], v[212:213], v[208:209]
	v_pk_fma_f32 v[198:199], v[188:189], v[140:141], v[198:199]
	v_add_f32_e32 v104, 1.0, v104
	v_add_f32_e32 v105, 1.0, v105
	v_rcp_f32_e32 v104, v104
	v_rcp_f32_e32 v105, v105
	v_pk_add_f32 v[208:209], v[130:131], v[208:209]
	v_pk_fma_f32 v[198:199], v[144:145], v[220:221], v[198:199]
	v_mul_f32_e32 v98, v98, v208
	v_mul_f32_e32 v99, v99, v209
	v_pk_add_f32 v[198:199], v[132:133], v[198:199]
	v_cvt_pk_bf16_f32 v98, v98, v99
	v_mul_f32_e32 v99, v100, v104
	v_mul_f32_e32 v100, v101, v105
	v_mul_f32_e32 v99, v99, v198
	v_mul_f32_e32 v100, v100, v199
	v_cvt_pk_bf16_f32 v99, v99, v100
	v_mov_b64_e32 v[100:101], s[30:31]
	v_mad_i64_i32 v[104:105], s[12:13], v194, s7, v[100:101]
	v_lshlrev_b64 v[194:195], 1, v[178:179]
	v_lshl_add_u64 v[104:105], v[104:105], 0, v[194:195]
	global_store_dwordx2 v[104:105], v[98:99], off
	v_cndmask_b32_e64 v99, v238, v200, s[38:39]
	v_cndmask_b32_e64 v107, v238, v112, s[42:43]
	v_mov_b32_e32 v98, v1
	v_mov_b32_e32 v106, v1
	v_cndmask_b32_e64 v193, v239, v113, s[42:43]
	v_mov_b32_dpp v98, v99 row_ror:1 row_mask:0xf bank_mask:0xf
	v_mov_b32_dpp v106, v107 row_ror:15 row_mask:0xf bank_mask:0xf
	v_cndmask_b32_e64 v107, v239, v201, s[38:39]
	v_mov_b32_e32 v99, v1
	v_cndmask_b32_e64 v199, v236, v110, s[42:43]
	v_mov_b32_e32 v198, v1
	v_mov_b32_dpp v99, v107 row_ror:1 row_mask:0xf bank_mask:0xf
	v_mov_b32_e32 v107, v1
	v_pk_mul_f32 v[98:99], v[122:123], v[98:99]
	v_mov_b32_dpp v198, v199 row_ror:15 row_mask:0xf bank_mask:0xf
	v_mov_b32_dpp v107, v193 row_ror:15 row_mask:0xf bank_mask:0xf
	v_cndmask_b32_e64 v193, v236, v196, s[38:39]
	v_mov_b32_e32 v196, v1
	v_pk_fma_f32 v[98:99], v[238:239], v[126:127], v[98:99]
	v_cndmask_b32_e64 v200, v237, v111, s[42:43]
; __device__ __forceinline__ unsigned cvt_pk_bf16(float lo, float hi) { unsigned r; asm volatile("v_cvt_pk_bf16_f32 %0, %1, %2" : "=v"(r) : "v"(lo), "v"(hi)); return r; }
; __device__ __forceinline__ float sigmoid_f(float x) { return fast_rcp(1.0f + fast_exp2(-1.4426950409f * x)); }
;     __device__ __forceinline__ void operator()(f32x4 (&acc)[2][2][4][2], const Unit& u, int wr, int wc, int fr, int fq) const {
;     ...
;             for (int ai = 0; ai < 2; ++ai) {
;                 const int grp = u.pm * 4 + ai * 2 + wr;
; #pragma unroll
;                 for (int m = 0; m < 4; ++m) {
;                     f32x4 cv[2];
; #pragma unroll
;                     for (int bj = 0; bj < 2; ++bj) {
;                         const f32x4 cur = acc[ai][bj][m][n], lo = acc[ai][bj][m > 0 ? m - 1 : 0][n], hi = acc[ai][bj][m < 3 ? m + 1 : 3][n];
;                         f32x4 pv, nv;
; #pragma unroll
;                         for (int idx = 0; idx < 4; ++idx) {
;                             const float y = (fr == 15) ? lo[idx] : cur[idx], z = (fr == 0) ? hi[idx] : cur[idx];
;                             pv[idx] = __int_as_float(__builtin_amdgcn_update_dpp(0, __float_as_int(y), 0x121, 0xf, 0xf, false));
;                             nv[idx] = __int_as_float(__builtin_amdgcn_update_dpp(0, __float_as_int(z), 0x12f, 0xf, 0xf, false));
;                         }
;                         cv[bj] = kc[bj][0] * pv + kc[bj][1] * cur + kc[bj][2] * nv + bc[bj];
;                     }
;                     const int row = row0 + ai * HALF + m * 16;
;                     const bool edge = (m == 0 && fr == 0) || (m == 3 && fr == 15);
;                     if (!edge) { const f32x4 gt = cv[0], vl = cv[1];
;                         u32x2 w; w.x = cvt_pk_bf16(gt[0] * sigmoid_f(gt[0]) * vl[0], gt[1] * sigmoid_f(gt[1]) * vl[1]); w.y = cvt_pk_bf16(gt[2] * sigmoid_f(gt[2]) * vl[2], gt[3] * sigmoid_f(gt[3]) * vl[3]);
;                         *(u32x2*)(ACT + (size_t)row * FF + j4) = w; }
	v_mov_b32_dpp v196, v193 row_ror:1 row_mask:0xf bank_mask:0xf
	v_cndmask_b32_e64 v193, v237, v197, s[38:39]
	v_mov_b32_e32 v197, v1
	v_pk_fma_f32 v[98:99], v[118:119], v[106:107], v[98:99]
	v_mov_b32_e32 v199, v1
	v_mov_b32_dpp v197, v193 row_ror:1 row_mask:0xf bank_mask:0xf
	v_cndmask_b32_e64 v193, v234, v190, s[38:39]
	v_mov_b32_e32 v190, v1
	v_pk_add_f32 v[98:99], v[114:115], v[98:99]
	v_mov_b32_dpp v199, v200 row_ror:15 row_mask:0xf bank_mask:0xf
	v_mov_b32_dpp v190, v193 row_ror:1 row_mask:0xf bank_mask:0xf
	v_cndmask_b32_e64 v193, v235, v191, s[38:39]
	v_mov_b32_e32 v191, v1
	v_mul_f32_e32 v106, 0xbfb8aa3b, v98
	v_cndmask_b32_e64 v201, v234, v108, s[42:43]
	v_mov_b32_dpp v191, v193 row_ror:1 row_mask:0xf bank_mask:0xf
	v_cndmask_b32_e64 v193, v232, v188, s[38:39]
	v_mov_b32_e32 v188, v1
	v_mov_b32_e32 v200, v1
	v_cndmask_b32_e64 v208, v235, v109, s[42:43]
	v_mov_b32_dpp v188, v193 row_ror:1 row_mask:0xf bank_mask:0xf
	v_cndmask_b32_e64 v193, v233, v189, s[38:39]
	v_mov_b32_e32 v189, v1
	v_mov_b32_dpp v200, v201 row_ror:15 row_mask:0xf bank_mask:0xf
	v_mov_b32_e32 v201, v1
	v_mov_b32_dpp v189, v193 row_ror:1 row_mask:0xf bank_mask:0xf
	v_exp_f32_e32 v193, v106
	v_pk_mul_f32 v[190:191], v[134:135], v[190:191]
	v_mov_b32_dpp v201, v208 row_ror:15 row_mask:0xf bank_mask:0xf
	v_pk_fma_f32 v[190:191], v[234:235], v[138:139], v[190:191]
	v_mul_f32_e32 v106, 0xbfb8aa3b, v99
	v_add_f32_e32 v193, 1.0, v193
	v_pk_fma_f32 v[190:191], v[142:143], v[200:201], v[190:191]
	v_exp_f32_e32 v200, v106
	v_rcp_f32_e32 v193, v193
	v_pk_mul_f32 v[196:197], v[124:125], v[196:197]
	v_pk_add_f32 v[190:191], v[130:131], v[190:191]
	v_pk_fma_f32 v[196:197], v[236:237], v[128:129], v[196:197]
	v_mul_f32_e32 v98, v98, v193
	v_pk_fma_f32 v[106:107], v[120:121], v[198:199], v[196:197]
	v_add_f32_e32 v196, 1.0, v200
	v_pk_add_f32 v[106:107], v[116:117], v[106:107]
	v_rcp_f32_e32 v196, v196
	v_mul_f32_e32 v98, v98, v190
	v_mul_f32_e32 v190, 0xbfb8aa3b, v106
	v_mul_f32_e32 v193, 0xbfb8aa3b, v107
	v_exp_f32_e32 v190, v190
	v_exp_f32_e32 v193, v193
	v_mul_f32_e32 v99, v99, v196
	v_mul_f32_e32 v99, v99, v191
	v_add_f32_e32 v190, 1.0, v190
	v_add_f32_e32 v191, 1.0, v193
	v_cndmask_b32_e64 v209, v232, v102, s[42:43]
	v_mov_b32_e32 v208, v1
	v_rcp_f32_e32 v190, v190
	v_rcp_f32_e32 v191, v191
	v_mov_b32_dpp v208, v209 row_ror:15 row_mask:0xf bank_mask:0xf
	v_cndmask_b32_e64 v212, v233, v103, s[42:43]
	v_mov_b32_e32 v209, v1
	v_pk_mul_f32 v[188:189], v[136:137], v[188:189]
	v_cvt_pk_bf16_f32 v98, v98, v99
	v_mul_f32_e32 v99, v106, v190
	v_mov_b32_dpp v209, v212 row_ror:15 row_mask:0xf bank_mask:0xf
	v_pk_fma_f32 v[188:189], v[232:233], v[140:141], v[188:189]
	v_mul_f32_e32 v106, v107, v191
	v_pk_fma_f32 v[188:189], v[144:145], v[208:209], v[188:189]
	v_mad_i64_i32 v[100:101], s[12:13], v192, s7, v[100:101]
	v_pk_add_f32 v[188:189], v[132:133], v[188:189]
	v_mov_b32_e32 v190, v1
	v_mul_f32_e32 v99, v99, v188
	v_mul_f32_e32 v106, v106, v189
	v_cvt_pk_bf16_f32 v99, v99, v106
	v_lshl_add_u64 v[106:107], v[100:101], 0, v[194:195]
	global_store_dwordx2 v[106:107], v[98:99], off
	v_cndmask_b32_e64 v98, v112, v238, s[38:39]
	v_mov_b32_e32 v188, v1
	v_mov_b32_e32 v189, v1
	v_cndmask_b32_e64 v99, v111, v237, s[38:39]
	v_mov_b32_dpp v188, v98 row_ror:1 row_mask:0xf bank_mask:0xf
	v_cndmask_b32_e64 v98, v113, v239, s[38:39]
	v_mov_b32_e32 v191, v1
	v_cndmask_b32_e64 v192, v108, v234, s[38:39]
	v_mov_b32_dpp v189, v98 row_ror:1 row_mask:0xf bank_mask:0xf
	v_cndmask_b32_e64 v98, v110, v236, s[38:39]
	v_mov_b32_e32 v196, v1
	v_cndmask_b32_e64 v193, v109, v235, s[38:39]
	v_mov_b32_e32 v197, v1
	v_cndmask_b32_e64 v198, v102, v232, s[38:39]
	v_mov_b32_e32 v200, v1
	v_cndmask_b32_e64 v199, v103, v233, s[38:39]
	v_mov_b32_e32 v201, v1
	v_mov_b32_e32 v100, v1
	v_mov_b32_e32 v101, v1
	v_mov_b32_dpp v190, v98 row_ror:1 row_mask:0xf bank_mask:0xf
	v_mov_b32_e32 v98, v1
	v_mov_b32_dpp v191, v99 row_ror:1 row_mask:0xf bank_mask:0xf
	v_mov_b32_e32 v99, v1
	v_mov_b32_dpp v196, v192 row_ror:1 row_mask:0xf bank_mask:0xf
	v_mov_b32_e32 v192, v1
	v_mov_b32_dpp v197, v193 row_ror:1 row_mask:0xf bank_mask:0xf
	v_mov_b32_e32 v193, v1
	v_mov_b32_dpp v200, v198 row_ror:1 row_mask:0xf bank_mask:0xf
	v_mov_b32_e32 v198, v1
	v_mov_b32_dpp v201, v199 row_ror:1 row_mask:0xf bank_mask:0xf
	v_mov_b32_e32 v199, v1
	v_mov_b32_dpp v100, v112 row_ror:15 row_mask:0xf bank_mask:0xf
	v_mov_b32_dpp v101, v113 row_ror:15 row_mask:0xf bank_mask:0xf
	v_mov_b32_dpp v98, v110 row_ror:15 row_mask:0xf bank_mask:0xf
	v_mov_b32_dpp v99, v111 row_ror:15 row_mask:0xf bank_mask:0xf
	v_mov_b32_dpp v192, v108 row_ror:15 row_mask:0xf bank_mask:0xf
	v_mov_b32_dpp v193, v109 row_ror:15 row_mask:0xf bank_mask:0xf
	v_mov_b32_dpp v198, v102 row_ror:15 row_mask:0xf bank_mask:0xf
	v_mov_b32_dpp v199, v103 row_ror:15 row_mask:0xf bank_mask:0xf
	s_and_saveexec_b64 s[12:13], s[40:41]
	s_movk_i32 s94, 0x1000
	s_movk_i32 s95, 0x3000
	s_cbranch_execz .LBB0_761
	v_pk_mul_f32 v[188:189], v[122:123], v[188:189]
	v_pk_mul_f32 v[190:191], v[124:125], v[190:191]
	v_pk_fma_f32 v[188:189], v[112:113], v[126:127], v[188:189]
	v_pk_fma_f32 v[190:191], v[110:111], v[128:129], v[190:191]
	v_pk_fma_f32 v[100:101], v[118:119], v[100:101], v[188:189]
	v_pk_fma_f32 v[98:99], v[120:121], v[98:99], v[190:191]
	v_pk_add_f32 v[100:101], v[114:115], v[100:101]
	v_pk_add_f32 v[98:99], v[116:117], v[98:99]
	v_mul_f32_e32 v188, 0xbfb8aa3b, v100
	v_mul_f32_e32 v189, 0xbfb8aa3b, v101
	v_exp_f32_e32 v188, v188
	v_exp_f32_e32 v189, v189
	v_pk_mul_f32 v[200:201], v[136:137], v[200:201]
	v_pk_mul_f32 v[196:197], v[134:135], v[196:197]
	v_add_f32_e32 v188, 1.0, v188
	v_add_f32_e32 v189, 1.0, v189
	v_rcp_f32_e32 v188, v188
	v_rcp_f32_e32 v189, v189
	v_pk_fma_f32 v[200:201], v[102:103], v[140:141], v[200:201]
	v_pk_fma_f32 v[196:197], v[108:109], v[138:139], v[196:197]
	v_mul_f32_e32 v100, v100, v188
	v_mul_f32_e32 v101, v101, v189
	v_mul_f32_e32 v188, 0xbfb8aa3b, v98
	v_mul_f32_e32 v189, 0xbfb8aa3b, v99
	v_exp_f32_e32 v188, v188
	v_exp_f32_e32 v189, v189
	v_pk_fma_f32 v[198:199], v[144:145], v[198:199], v[200:201]
	v_pk_fma_f32 v[192:193], v[142:143], v[192:193], v[196:197]
	v_add_f32_e32 v188, 1.0, v188
	v_add_f32_e32 v189, 1.0, v189
	v_rcp_f32_e32 v188, v188
	v_rcp_f32_e32 v189, v189
	v_pk_add_f32 v[192:193], v[130:131], v[192:193]
	v_pk_add_f32 v[196:197], v[132:133], v[198:199]
	v_mul_f32_e32 v98, v98, v188
	v_mul_f32_e32 v99, v99, v189
	v_mul_f32_e32 v100, v100, v192
	v_mul_f32_e32 v101, v101, v193
	v_mul_f32_e32 v98, v98, v196
	v_mul_f32_e32 v99, v99, v197
	v_cvt_pk_bf16_f32 v100, v100, v101
	v_cvt_pk_bf16_f32 v101, v98, v99
	v_mov_b64_e32 v[98:99], s[30:31]
	v_mad_i64_i32 v[98:99], s[34:35], v160, s7, v[98:99]
	v_lshl_add_u64 v[98:99], v[178:179], 1, v[98:99]
	global_store_dwordx2 v[98:99], v[100:101], off

; __device__ __forceinline__ unsigned cvt_pk_bf16(float lo, float hi) { unsigned r; asm volatile("v_cvt_pk_bf16_f32 %0, %1, %2" : "=v"(r) : "v"(lo), "v"(hi)); return r; }
; __device__ __forceinline__ float sigmoid_f(float x) { return fast_rcp(1.0f + fast_exp2(-1.4426950409f * x)); }
;     __device__ __forceinline__ void operator()(f32x4 (&acc)[2][2][4][2], const Unit& u, int wr, int wc, int fr, int fq) const {
;     ...
;             for (int ai = 0; ai < 2; ++ai) {
;                 const int grp = u.pm * 4 + ai * 2 + wr;
; #pragma unroll
;                 for (int m = 0; m < 4; ++m) {
;                     f32x4 cv[2];
; #pragma unroll
;                     for (int bj = 0; bj < 2; ++bj) {
;                         const f32x4 cur = acc[ai][bj][m][n], lo = acc[ai][bj][m > 0 ? m - 1 : 0][n], hi = acc[ai][bj][m < 3 ? m + 1 : 3][n];
;                         f32x4 pv, nv;
; #pragma unroll
;                         for (int idx = 0; idx < 4; ++idx) {
;                             const float y = (fr == 15) ? lo[idx] : cur[idx], z = (fr == 0) ? hi[idx] : cur[idx];
;                             pv[idx] = __int_as_float(__builtin_amdgcn_update_dpp(0, __float_as_int(y), 0x121, 0xf, 0xf, false));
;                             nv[idx] = __int_as_float(__builtin_amdgcn_update_dpp(0, __float_as_int(z), 0x12f, 0xf, 0xf, false));
;                         }
;                         cv[bj] = kc[bj][0] * pv + kc[bj][1] * cur + kc[bj][2] * nv + bc[bj];
;                     }
;                     const int row = row0 + ai * HALF + m * 16;
;                     const bool edge = (m == 0 && fr == 0) || (m == 3 && fr == 15);
;                     if (!edge) { const f32x4 gt = cv[0], vl = cv[1];
;                         u32x2 w; w.x = cvt_pk_bf16(gt[0] * sigmoid_f(gt[0]) * vl[0], gt[1] * sigmoid_f(gt[1]) * vl[1]); w.y = cvt_pk_bf16(gt[2] * sigmoid_f(gt[2]) * vl[2], gt[3] * sigmoid_f(gt[3]) * vl[3]);
;                         *(u32x2*)(ACT + (size_t)row * FF + j4) = w; }
.LBB0_763:
	s_or_b64 exec, exec, s[12:13]
	v_mov_b32_e32 v108, 1.0
	v_mov_b32_e32 v110, 1.0
	v_pk_mul_f32 v[196:197], v[94:95], v[108:109] op_sel_hi:[1,0]
	v_pk_mul_f32 v[94:95], v[88:89], v[108:109] op_sel_hi:[1,0]
	v_pk_mul_f32 v[192:193], v[96:97], v[108:109] op_sel_hi:[1,0]
	v_pk_mul_f32 v[88:89], v[90:91], v[110:111] op_sel_hi:[1,0]
	v_pk_mul_f32 v[96:97], v[86:87], v[108:109] op_sel_hi:[1,0]
	v_pk_mul_f32 v[86:87], v[92:93], v[110:111] op_sel_hi:[1,0]
	v_cndmask_b32_e64 v90, v196, v88, s[42:43]
	v_mov_b32_e32 v92, v1
	v_mov_b32_e32 v93, v1
	v_cndmask_b32_e64 v91, v192, v86, s[42:43]
	v_mov_b32_dpp v92, v90 row_ror:15 row_mask:0xf bank_mask:0xf
	v_cndmask_b32_e64 v90, v197, v89, s[42:43]
	v_pk_mul_f32 v[82:83], v[82:83], v[110:111] op_sel_hi:[1,0]
	v_cndmask_b32_e64 v109, v193, v87, s[42:43]
	v_mov_b32_dpp v93, v90 row_ror:15 row_mask:0xf bank_mask:0xf
	v_mov_b32_e32 v90, v1
	v_mov_b32_e32 v188, v1
	v_pk_mul_f32 v[84:85], v[84:85], v[110:111] op_sel_hi:[1,0]
	v_mov_b32_dpp v90, v91 row_ror:15 row_mask:0xf bank_mask:0xf
	v_mov_b32_e32 v91, v1
	v_mov_b32_e32 v189, v1
	v_mov_b32_e32 v198, v1
	v_mov_b32_dpp v91, v109 row_ror:15 row_mask:0xf bank_mask:0xf
	v_cndmask_b32_e64 v109, v96, v82, s[42:43]
	v_mov_b32_e32 v102, v1
	v_mov_b32_e32 v103, v1
	v_mov_b32_dpp v188, v109 row_ror:15 row_mask:0xf bank_mask:0xf
	v_cndmask_b32_e64 v109, v97, v83, s[42:43]
	v_mov_b32_e32 v112, v1
	v_mov_b32_e32 v113, v1
	v_mov_b32_dpp v189, v109 row_ror:15 row_mask:0xf bank_mask:0xf
	v_cndmask_b32_e64 v109, v94, v84, s[42:43]
	v_mov_b32_e32 v190, v1
	v_mov_b32_e32 v191, v1
	v_mov_b32_e32 v200, v1
	v_mov_b32_dpp v198, v109 row_ror:15 row_mask:0xf bank_mask:0xf
	v_cndmask_b32_e64 v109, v95, v85, s[42:43]
	v_mov_b32_e32 v201, v1
	v_mov_b32_e32 v199, v1
	v_mov_b32_dpp v102, v196 row_ror:1 row_mask:0xf bank_mask:0xf
	v_mov_b32_dpp v103, v197 row_ror:1 row_mask:0xf bank_mask:0xf
	v_mov_b32_dpp v112, v192 row_ror:1 row_mask:0xf bank_mask:0xf
	v_mov_b32_dpp v113, v193 row_ror:1 row_mask:0xf bank_mask:0xf
	v_mov_b32_dpp v190, v96 row_ror:1 row_mask:0xf bank_mask:0xf
	v_mov_b32_dpp v191, v97 row_ror:1 row_mask:0xf bank_mask:0xf
	v_mov_b32_dpp v200, v94 row_ror:1 row_mask:0xf bank_mask:0xf
	v_mov_b32_dpp v201, v95 row_ror:1 row_mask:0xf bank_mask:0xf
	v_mov_b32_dpp v199, v109 row_ror:15 row_mask:0xf bank_mask:0xf
	s_and_saveexec_b64 s[12:13], s[44:45]
	s_cbranch_execz .LBB0_765
	v_pk_mul_f32 v[102:103], v[122:123], v[102:103]
	v_pk_mul_f32 v[112:113], v[124:125], v[112:113]
	v_pk_fma_f32 v[102:103], v[196:197], v[126:127], v[102:103]
	v_pk_fma_f32 v[112:113], v[192:193], v[128:129], v[112:113]
	v_pk_fma_f32 v[92:93], v[118:119], v[92:93], v[102:103]
	v_pk_fma_f32 v[90:91], v[120:121], v[90:91], v[112:113]
	v_pk_add_f32 v[92:93], v[114:115], v[92:93]
	v_pk_add_f32 v[90:91], v[116:117], v[90:91]
	v_mul_f32_e32 v102, 0xbfb8aa3b, v92
	v_mul_f32_e32 v103, 0xbfb8aa3b, v93
	v_exp_f32_e32 v102, v102
	v_exp_f32_e32 v103, v103
	v_pk_mul_f32 v[200:201], v[136:137], v[200:201]
	v_pk_mul_f32 v[190:191], v[134:135], v[190:191]
	v_add_f32_e32 v102, 1.0, v102
	v_add_f32_e32 v103, 1.0, v103
	v_rcp_f32_e32 v102, v102
	v_rcp_f32_e32 v103, v103
	v_pk_fma_f32 v[200:201], v[94:95], v[140:141], v[200:201]
	v_pk_fma_f32 v[190:191], v[96:97], v[138:139], v[190:191]
	v_mul_f32_e32 v92, v92, v102
	v_mul_f32_e32 v93, v93, v103
	v_mul_f32_e32 v102, 0xbfb8aa3b, v90
	v_mul_f32_e32 v103, 0xbfb8aa3b, v91
	v_exp_f32_e32 v102, v102
	v_exp_f32_e32 v103, v103
	v_pk_fma_f32 v[198:199], v[144:145], v[198:199], v[200:201]
	v_pk_fma_f32 v[188:189], v[142:143], v[188:189], v[190:191]
	v_add_f32_e32 v102, 1.0, v102
	v_add_f32_e32 v103, 1.0, v103
	v_rcp_f32_e32 v102, v102
	v_rcp_f32_e32 v103, v103
	v_pk_add_f32 v[188:189], v[130:131], v[188:189]
	v_pk_add_f32 v[190:191], v[132:133], v[198:199]
	v_mul_f32_e32 v90, v90, v102
	v_mul_f32_e32 v91, v91, v103
	v_mul_f32_e32 v92, v92, v188
	v_mul_f32_e32 v93, v93, v189
	v_mul_f32_e32 v90, v90, v190
	v_mul_f32_e32 v91, v91, v191
	v_cvt_pk_bf16_f32 v92, v92, v93
	v_cvt_pk_bf16_f32 v93, v90, v91
	v_mov_b64_e32 v[90:91], s[30:31]
	v_mad_i64_i32 v[90:91], s[34:35], v158, s7, v[90:91]
	v_lshl_add_u64 v[90:91], v[178:179], 1, v[90:91]
	global_store_dwordx2 v[90:91], v[92:93], off

; __device__ __forceinline__ unsigned cvt_pk_bf16(float lo, float hi) { unsigned r; asm volatile("v_cvt_pk_bf16_f32 %0, %1, %2" : "=v"(r) : "v"(lo), "v"(hi)); return r; }
; __device__ __forceinline__ float sigmoid_f(float x) { return fast_rcp(1.0f + fast_exp2(-1.4426950409f * x)); }
;     __device__ __forceinline__ void operator()(f32x4 (&acc)[2][2][4][2], const Unit& u, int wr, int wc, int fr, int fq) const {
;     ...
;             for (int ai = 0; ai < 2; ++ai) {
;                 const int grp = u.pm * 4 + ai * 2 + wr;
; #pragma unroll
;                 for (int m = 0; m < 4; ++m) {
;                     f32x4 cv[2];
; #pragma unroll
;                     for (int bj = 0; bj < 2; ++bj) {
;                         const f32x4 cur = acc[ai][bj][m][n], lo = acc[ai][bj][m > 0 ? m - 1 : 0][n], hi = acc[ai][bj][m < 3 ? m + 1 : 3][n];
;                         f32x4 pv, nv;
; #pragma unroll
;                         for (int idx = 0; idx < 4; ++idx) {
;                             const float y = (fr == 15) ? lo[idx] : cur[idx], z = (fr == 0) ? hi[idx] : cur[idx];
;                             pv[idx] = __int_as_float(__builtin_amdgcn_update_dpp(0, __float_as_int(y), 0x121, 0xf, 0xf, false));
;                             nv[idx] = __int_as_float(__builtin_amdgcn_update_dpp(0, __float_as_int(z), 0x12f, 0xf, 0xf, false));
;                         }
;                         cv[bj] = kc[bj][0] * pv + kc[bj][1] * cur + kc[bj][2] * nv + bc[bj];
;                     }
;                     const int row = row0 + ai * HALF + m * 16;
;                     const bool edge = (m == 0 && fr == 0) || (m == 3 && fr == 15);
;                     if (!edge) { const f32x4 gt = cv[0], vl = cv[1];
;                         u32x2 w; w.x = cvt_pk_bf16(gt[0] * sigmoid_f(gt[0]) * vl[0], gt[1] * sigmoid_f(gt[1]) * vl[1]); w.y = cvt_pk_bf16(gt[2] * sigmoid_f(gt[2]) * vl[2], gt[3] * sigmoid_f(gt[3]) * vl[3]);
;                         *(u32x2*)(ACT + (size_t)row * FF + j4) = w; }
.LBB0_767:
	s_or_b64 exec, exec, s[12:13]
	v_mov_b32_e32 v188, 1.0
	s_waitcnt lgkmcnt(0)
	v_mov_b32_e32 v190, 1.0
	v_pk_mul_f32 v[92:93], v[78:79], v[188:189] op_sel_hi:[1,0]
	v_pk_mul_f32 v[90:91], v[80:81], v[188:189] op_sel_hi:[1,0]
	v_pk_mul_f32 v[78:79], v[72:73], v[188:189] op_sel_hi:[1,0]
	v_pk_mul_f32 v[80:81], v[70:71], v[188:189] op_sel_hi:[1,0]
	v_pk_mul_f32 v[70:71], v[76:77], v[190:191] op_sel_hi:[1,0]
	v_pk_mul_f32 v[72:73], v[74:75], v[190:191] op_sel_hi:[1,0]
	v_cndmask_b32_e64 v75, v88, v196, s[38:39]
	v_cndmask_b32_e64 v77, v88, v92, s[42:43]
	v_mov_b32_e32 v74, v1
	v_mov_b32_e32 v76, v1
	v_cndmask_b32_e64 v109, v89, v93, s[42:43]
	v_mov_b32_dpp v74, v75 row_ror:1 row_mask:0xf bank_mask:0xf
	v_mov_b32_dpp v76, v77 row_ror:15 row_mask:0xf bank_mask:0xf
	v_cndmask_b32_e64 v77, v89, v197, s[38:39]
	v_mov_b32_e32 v75, v1
	v_cndmask_b32_e64 v111, v86, v90, s[42:43]
	v_mov_b32_e32 v196, v1
	v_mov_b32_dpp v75, v77 row_ror:1 row_mask:0xf bank_mask:0xf
	v_mov_b32_e32 v77, v1
	v_pk_mul_f32 v[74:75], v[122:123], v[74:75]
	v_mov_b32_dpp v196, v111 row_ror:15 row_mask:0xf bank_mask:0xf
	v_mov_b32_dpp v77, v109 row_ror:15 row_mask:0xf bank_mask:0xf
	v_cndmask_b32_e64 v109, v86, v192, s[38:39]
	v_mov_b32_e32 v192, v1
	v_pk_fma_f32 v[74:75], v[126:127], v[88:89], v[74:75]
	v_cndmask_b32_e64 v111, v87, v91, s[42:43]
	v_mov_b32_dpp v192, v109 row_ror:1 row_mask:0xf bank_mask:0xf
	v_cndmask_b32_e64 v109, v87, v193, s[38:39]
	v_mov_b32_e32 v193, v1
	v_pk_fma_f32 v[74:75], v[118:119], v[76:77], v[74:75]
	v_mov_b32_e32 v197, v1
	v_mov_b32_dpp v193, v109 row_ror:1 row_mask:0xf bank_mask:0xf
	v_cndmask_b32_e64 v109, v82, v96, s[38:39]
	v_mov_b32_e32 v96, v1
	v_pk_add_f32 v[74:75], v[114:115], v[74:75]
	v_mov_b32_dpp v197, v111 row_ror:15 row_mask:0xf bank_mask:0xf
	v_mov_b32_dpp v96, v109 row_ror:1 row_mask:0xf bank_mask:0xf
	v_cndmask_b32_e64 v109, v83, v97, s[38:39]
	v_mov_b32_e32 v97, v1
	v_mul_f32_e32 v76, 0xbfb8aa3b, v74
	v_cndmask_b32_e64 v111, v82, v80, s[42:43]
	v_mov_b32_dpp v97, v109 row_ror:1 row_mask:0xf bank_mask:0xf
	v_cndmask_b32_e64 v109, v84, v94, s[38:39]
	v_mov_b32_e32 v94, v1
	v_mov_b32_e32 v198, v1
	v_mov_b32_e32 v199, v1
	v_mov_b32_dpp v94, v109 row_ror:1 row_mask:0xf bank_mask:0xf
	v_cndmask_b32_e64 v109, v85, v95, s[38:39]
	v_mov_b32_e32 v95, v1
	v_mov_b32_dpp v198, v111 row_ror:15 row_mask:0xf bank_mask:0xf
	v_cndmask_b32_e64 v111, v83, v81, s[42:43]
	v_mov_b32_dpp v95, v109 row_ror:1 row_mask:0xf bank_mask:0xf
	v_exp_f32_e32 v109, v76
	v_mov_b32_dpp v199, v111 row_ror:15 row_mask:0xf bank_mask:0xf
	v_cndmask_b32_e64 v111, v84, v78, s[42:43]
	v_mov_b32_e32 v200, v1
	v_mov_b32_e32 v201, v1
	v_mul_f32_e32 v76, 0xbfb8aa3b, v75
	v_mov_b32_dpp v200, v111 row_ror:15 row_mask:0xf bank_mask:0xf
	v_cndmask_b32_e64 v111, v85, v79, s[42:43]
	v_add_f32_e32 v109, 1.0, v109
	v_rcp_f32_e32 v109, v109
	v_mov_b32_dpp v201, v111 row_ror:15 row_mask:0xf bank_mask:0xf
	v_exp_f32_e32 v111, v76
	v_pk_mul_f32 v[96:97], v[134:135], v[96:97]
	v_pk_mul_f32 v[192:193], v[124:125], v[192:193]
	v_pk_fma_f32 v[96:97], v[82:83], v[138:139], v[96:97]
	v_pk_fma_f32 v[192:193], v[128:129], v[86:87], v[192:193]
	v_pk_fma_f32 v[96:97], v[142:143], v[198:199], v[96:97]
	v_pk_fma_f32 v[76:77], v[120:121], v[196:197], v[192:193]
	v_pk_add_f32 v[96:97], v[130:131], v[96:97]
	v_add_f32_e32 v111, 1.0, v111
	v_pk_add_f32 v[76:77], v[116:117], v[76:77]
	v_mul_f32_e32 v74, v74, v109
	v_rcp_f32_e32 v111, v111
	v_mul_f32_e32 v74, v74, v96
	v_mul_f32_e32 v96, 0xbfb8aa3b, v76
	v_mul_f32_e32 v109, 0xbfb8aa3b, v77
	v_exp_f32_e32 v96, v96
	v_exp_f32_e32 v109, v109
	v_mul_f32_e32 v75, v75, v111
	v_mul_f32_e32 v75, v75, v97
	v_add_f32_e32 v96, 1.0, v96
	v_add_f32_e32 v97, 1.0, v109
	v_rcp_f32_e32 v96, v96
	v_rcp_f32_e32 v97, v97
	v_pk_mul_f32 v[94:95], v[136:137], v[94:95]
	v_cvt_pk_bf16_f32 v74, v74, v75
	v_mul_f32_e32 v75, v76, v96
	v_pk_fma_f32 v[94:95], v[84:85], v[140:141], v[94:95]
	v_mul_f32_e32 v76, v77, v97
	v_pk_fma_f32 v[94:95], v[144:145], v[200:201], v[94:95]
	v_cndmask_b32_e64 v89, v93, v89, s[38:39]
	v_pk_add_f32 v[94:95], v[132:133], v[94:95]
	v_cndmask_b32_e64 v96, v91, v71, s[42:43]
	v_mul_f32_e32 v75, v75, v94
	v_mul_f32_e32 v76, v76, v95
	v_cvt_pk_bf16_f32 v75, v75, v76
	v_mov_b64_e32 v[76:77], s[30:31]
	v_mad_i64_i32 v[94:95], s[12:13], v186, s7, v[76:77]
	v_lshl_add_u64 v[186:187], v[94:95], 0, v[194:195]
	global_store_dwordx2 v[186:187], v[74:75], off
	v_cndmask_b32_e64 v75, v92, v88, s[38:39]
	v_mov_b32_e32 v74, v1
	v_cndmask_b32_e64 v94, v92, v72, s[42:43]
	v_mov_b32_e32 v88, v1
	v_mov_b32_dpp v74, v75 row_ror:1 row_mask:0xf bank_mask:0xf
	v_mov_b32_e32 v75, v1
	v_mov_b32_dpp v88, v94 row_ror:15 row_mask:0xf bank_mask:0xf
	v_cndmask_b32_e64 v94, v93, v73, s[42:43]
	v_mov_b32_dpp v75, v89 row_ror:1 row_mask:0xf bank_mask:0xf
	v_mov_b32_e32 v89, v1
	v_pk_mul_f32 v[74:75], v[122:123], v[74:75]
	v_cndmask_b32_e64 v95, v90, v70, s[42:43]
	v_mov_b32_dpp v89, v94 row_ror:15 row_mask:0xf bank_mask:0xf
	v_pk_fma_f32 v[74:75], v[126:127], v[92:93], v[74:75]
	v_cndmask_b32_e64 v94, v90, v86, s[38:39]
	v_pk_fma_f32 v[74:75], v[118:119], v[88:89], v[74:75]
	v_mov_b32_e32 v86, v1
	v_pk_add_f32 v[74:75], v[114:115], v[74:75]
	v_pk_mul_f32 v[66:67], v[66:67], v[190:191] op_sel_hi:[1,0]
	v_mov_b32_dpp v86, v94 row_ror:1 row_mask:0xf bank_mask:0xf
	v_mov_b32_e32 v94, v1
	v_mul_f32_e32 v88, 0xbfb8aa3b, v74
	v_exp_f32_e32 v88, v88
	v_mov_b32_dpp v94, v95 row_ror:15 row_mask:0xf bank_mask:0xf
	v_cndmask_b32_e64 v95, v91, v87, s[38:39]
	v_mov_b32_e32 v87, v1
	v_cndmask_b32_e64 v97, v80, v66, s[42:43]
	v_mul_f32_e32 v89, 0xbfb8aa3b, v75
;     __device__ __forceinline__ void operator()(f32x4 (&acc)[2][2][4][2], const Unit& u, int wr, int wc, int fr, int fq) const {
;     ...
;             for (int ai = 0; ai < 2; ++ai) {
;                 const int grp = u.pm * 4 + ai * 2 + wr;
; #pragma unroll
;                 for (int m = 0; m < 4; ++m) {
;                     f32x4 cv[2];
; #pragma unroll
;                     for (int bj = 0; bj < 2; ++bj) {
;                         const f32x4 cur = acc[ai][bj][m][n], lo = acc[ai][bj][m > 0 ? m - 1 : 0][n], hi = acc[ai][bj][m < 3 ? m + 1 : 3][n];
;                         f32x4 pv, nv;
; #pragma unroll
;                         for (int idx = 0; idx < 4; ++idx) {
;                             const float y = (fr == 15) ? lo[idx] : cur[idx], z = (fr == 0) ? hi[idx] : cur[idx];
;                             pv[idx] = __int_as_float(__builtin_amdgcn_update_dpp(0, __float_as_int(y), 0x121, 0xf, 0xf, false));
;                             nv[idx] = __int_as_float(__builtin_amdgcn_update_dpp(0, __float_as_int(z), 0x12f, 0xf, 0xf, false));
;                         }
;                         cv[bj] = kc[bj][0] * pv + kc[bj][1] * cur + kc[bj][2] * nv + bc[bj];
;                     }
;                     const int row = row0 + ai * HALF + m * 16;
;                     const bool edge = (m == 0 && fr == 0) || (m == 3 && fr == 15);
;                     if (!edge) { const f32x4 gt = cv[0], vl = cv[1];
;                         u32x2 w; w.x = cvt_pk_bf16(gt[0] * sigmoid_f(gt[0]) * vl[0], gt[1] * sigmoid_f(gt[1]) * vl[1]); w.y = cvt_pk_bf16(gt[2] * sigmoid_f(gt[2]) * vl[2], gt[3] * sigmoid_f(gt[3]) * vl[3]);
;                         *(u32x2*)(ACT + (size_t)row * FF + j4) = w; }
;                     if (m == 0 && fr < 2) {
; #pragma unroll
;                         for (int bj = 0; bj < 2; ++bj) { const f32x4 v = acc[ai][bj][0][n]; u32x2 w; w.x = cvt_pk_bf16(v[0], v[1]); w.y = cvt_pk_bf16(v[2], v[3]); *(u32x2*)(RAW + ((size_t)(grp * 4 + fr)) * NUP + bj * FF + j4) = w; } }
;                     if (m == 3 && fr >= 14) {
; #pragma unroll
;                         for (int bj = 0; bj < 2; ++bj) { const f32x4 v = acc[ai][bj][3][n]; u32x2 w; w.x = cvt_pk_bf16(v[0], v[1]); w.y = cvt_pk_bf16(v[2], v[3]); *(u32x2*)(RAW + ((size_t)(grp * 4 + 2 + (fr - 14))) * NUP + bj * FF + j4) = w; } }
	v_mov_b32_dpp v87, v95 row_ror:1 row_mask:0xf bank_mask:0xf
	v_mov_b32_e32 v95, v1
	v_add_f32_e32 v88, 1.0, v88
	v_exp_f32_e32 v89, v89
	v_mov_b32_dpp v95, v96 row_ror:15 row_mask:0xf bank_mask:0xf
	v_cndmask_b32_e64 v96, v80, v82, s[38:39]
	v_mov_b32_e32 v82, v1
	v_rcp_f32_e32 v88, v88
	v_cndmask_b32_e64 v109, v81, v67, s[42:43]
	v_mov_b32_dpp v82, v96 row_ror:1 row_mask:0xf bank_mask:0xf
	v_mov_b32_e32 v96, v1
	v_pk_mul_f32 v[86:87], v[124:125], v[86:87]
	v_add_f32_e32 v89, 1.0, v89
	v_mov_b32_dpp v96, v97 row_ror:15 row_mask:0xf bank_mask:0xf
	v_cndmask_b32_e64 v97, v81, v83, s[38:39]
	v_mov_b32_e32 v83, v1
	v_pk_fma_f32 v[86:87], v[128:129], v[90:91], v[86:87]
	v_mul_f32_e32 v74, v74, v88
	v_mov_b32_dpp v83, v97 row_ror:1 row_mask:0xf bank_mask:0xf
	v_mov_b32_e32 v97, v1
	v_pk_mul_f32 v[82:83], v[134:135], v[82:83]
	v_pk_fma_f32 v[86:87], v[120:121], v[94:95], v[86:87]
	v_mov_b32_dpp v97, v109 row_ror:15 row_mask:0xf bank_mask:0xf
	v_pk_fma_f32 v[82:83], v[138:139], v[80:81], v[82:83]
	v_pk_add_f32 v[86:87], v[116:117], v[86:87]
	v_pk_fma_f32 v[82:83], v[142:143], v[96:97], v[82:83]
	v_rcp_f32_e32 v89, v89
	v_pk_add_f32 v[82:83], v[130:131], v[82:83]
	v_mul_f32_e32 v88, 0xbfb8aa3b, v87
	v_mul_f32_e32 v74, v74, v82
	v_mul_f32_e32 v82, 0xbfb8aa3b, v86
	v_exp_f32_e32 v82, v82
	v_exp_f32_e32 v88, v88
	v_cndmask_b32_e64 v109, v78, v84, s[38:39]
	v_mov_b32_e32 v84, v1
	v_mul_f32_e32 v75, v75, v89
	v_pk_mul_f32 v[68:69], v[68:69], v[190:191] op_sel_hi:[1,0]
	v_mov_b32_dpp v84, v109 row_ror:1 row_mask:0xf bank_mask:0xf
	v_cndmask_b32_e64 v109, v79, v85, s[38:39]
	v_mov_b32_e32 v85, v1
	v_mul_f32_e32 v75, v75, v83
	v_add_f32_e32 v82, 1.0, v82
	v_add_f32_e32 v83, 1.0, v88
	v_cndmask_b32_e64 v111, v78, v68, s[42:43]
	v_mov_b32_e32 v192, v1
	v_mov_b32_dpp v85, v109 row_ror:1 row_mask:0xf bank_mask:0xf
	v_rcp_f32_e32 v82, v82
	v_rcp_f32_e32 v83, v83
	v_mov_b32_dpp v192, v111 row_ror:15 row_mask:0xf bank_mask:0xf
	v_cndmask_b32_e64 v111, v79, v69, s[42:43]
	v_mov_b32_e32 v193, v1
	v_pk_mul_f32 v[84:85], v[136:137], v[84:85]
	v_cvt_pk_bf16_f32 v74, v74, v75
	v_mul_f32_e32 v75, v86, v82
	v_mov_b32_dpp v193, v111 row_ror:15 row_mask:0xf bank_mask:0xf
	v_pk_fma_f32 v[84:85], v[140:141], v[78:79], v[84:85]
	v_mul_f32_e32 v82, v87, v83
	v_pk_fma_f32 v[84:85], v[144:145], v[192:193], v[84:85]
	v_mad_i64_i32 v[76:77], s[12:13], v184, s7, v[76:77]
	v_pk_add_f32 v[84:85], v[132:133], v[84:85]
	v_lshl_add_u64 v[184:185], v[76:77], 0, v[194:195]
	v_mul_f32_e32 v75, v75, v84
	v_mul_f32_e32 v82, v82, v85
	v_cvt_pk_bf16_f32 v75, v75, v82
	global_store_dwordx2 v[184:185], v[74:75], off
	v_cndmask_b32_e64 v74, v72, v92, s[38:39]
	v_mov_b32_e32 v82, v1
	v_mov_b32_e32 v83, v1
	v_mov_b32_e32 v84, v1
	v_mov_b32_dpp v82, v74 row_ror:1 row_mask:0xf bank_mask:0xf
	v_cndmask_b32_e64 v74, v73, v93, s[38:39]
	v_cndmask_b32_e64 v75, v71, v91, s[38:39]
	v_mov_b32_e32 v85, v1
	v_mov_b32_dpp v83, v74 row_ror:1 row_mask:0xf bank_mask:0xf
	v_cndmask_b32_e64 v74, v70, v90, s[38:39]
	v_cndmask_b32_e64 v80, v66, v80, s[38:39]
	v_mov_b32_e32 v86, v1
	v_cndmask_b32_e64 v81, v67, v81, s[38:39]
	v_mov_b32_e32 v87, v1
	v_cndmask_b32_e64 v78, v68, v78, s[38:39]
	v_mov_b32_e32 v88, v1
	v_cndmask_b32_e64 v79, v69, v79, s[38:39]
	v_mov_b32_e32 v89, v1
	v_mov_b32_e32 v76, v1
	v_mov_b32_e32 v77, v1
	v_mov_b32_dpp v84, v74 row_ror:1 row_mask:0xf bank_mask:0xf
	v_mov_b32_e32 v74, v1
	v_mov_b32_dpp v85, v75 row_ror:1 row_mask:0xf bank_mask:0xf
	v_mov_b32_e32 v75, v1
	v_mov_b32_dpp v86, v80 row_ror:1 row_mask:0xf bank_mask:0xf
	v_mov_b32_e32 v80, v1
	v_mov_b32_dpp v87, v81 row_ror:1 row_mask:0xf bank_mask:0xf
	v_mov_b32_e32 v81, v1
	v_mov_b32_dpp v88, v78 row_ror:1 row_mask:0xf bank_mask:0xf
	v_mov_b32_e32 v78, v1
	v_mov_b32_dpp v89, v79 row_ror:1 row_mask:0xf bank_mask:0xf
	v_mov_b32_e32 v79, v1
	v_mov_b32_dpp v76, v72 row_ror:15 row_mask:0xf bank_mask:0xf
	v_mov_b32_dpp v77, v73 row_ror:15 row_mask:0xf bank_mask:0xf
	v_mov_b32_dpp v74, v70 row_ror:15 row_mask:0xf bank_mask:0xf
	v_mov_b32_dpp v75, v71 row_ror:15 row_mask:0xf bank_mask:0xf
	v_mov_b32_dpp v80, v66 row_ror:15 row_mask:0xf bank_mask:0xf
	v_mov_b32_dpp v81, v67 row_ror:15 row_mask:0xf bank_mask:0xf
	v_mov_b32_dpp v78, v68 row_ror:15 row_mask:0xf bank_mask:0xf
	v_mov_b32_dpp v79, v69 row_ror:15 row_mask:0xf bank_mask:0xf
	s_and_saveexec_b64 s[12:13], s[40:41]
	s_cbranch_execz .LBB0_769
	v_pk_mul_f32 v[82:83], v[122:123], v[82:83]
	v_pk_mul_f32 v[86:87], v[134:135], v[86:87]
	v_pk_fma_f32 v[82:83], v[126:127], v[72:73], v[82:83]
	v_pk_mul_f32 v[84:85], v[124:125], v[84:85]
	v_pk_fma_f32 v[76:77], v[118:119], v[76:77], v[82:83]
	v_pk_fma_f32 v[86:87], v[138:139], v[66:67], v[86:87]
	v_pk_add_f32 v[76:77], v[114:115], v[76:77]
	v_pk_fma_f32 v[84:85], v[128:129], v[70:71], v[84:85]
	v_mul_f32_e32 v82, 0xbfb8aa3b, v76
	v_exp_f32_e32 v82, v82
	v_mul_f32_e32 v83, 0xbfb8aa3b, v77
	v_exp_f32_e32 v83, v83
	v_pk_fma_f32 v[80:81], v[142:143], v[80:81], v[86:87]
	v_add_f32_e32 v82, 1.0, v82
	v_rcp_f32_e32 v82, v82
	v_pk_fma_f32 v[74:75], v[120:121], v[74:75], v[84:85]
	v_pk_add_f32 v[80:81], v[130:131], v[80:81]
	v_add_f32_e32 v83, 1.0, v83
	v_pk_add_f32 v[74:75], v[116:117], v[74:75]
	v_mul_f32_e32 v76, v76, v82
	v_rcp_f32_e32 v83, v83
	v_mul_f32_e32 v76, v76, v80
	v_mul_f32_e32 v80, 0xbfb8aa3b, v74
	v_mul_f32_e32 v82, 0xbfb8aa3b, v75
	v_exp_f32_e32 v80, v80
	v_exp_f32_e32 v82, v82
	v_mul_f32_e32 v77, v77, v83
	v_mul_f32_e32 v77, v77, v81
	v_add_f32_e32 v80, 1.0, v80
	v_add_f32_e32 v81, 1.0, v82
	v_rcp_f32_e32 v80, v80
	v_rcp_f32_e32 v81, v81
	v_pk_mul_f32 v[88:89], v[136:137], v[88:89]
	v_cvt_pk_bf16_f32 v76, v76, v77
	v_mul_f32_e32 v74, v74, v80
	v_pk_fma_f32 v[88:89], v[140:141], v[68:69], v[88:89]
	v_mul_f32_e32 v75, v75, v81
	v_pk_fma_f32 v[78:79], v[144:145], v[78:79], v[88:89]
	s_nop 0
	v_pk_add_f32 v[78:79], v[132:133], v[78:79]
	s_nop 0
	v_mul_f32_e32 v74, v74, v78
	v_mul_f32_e32 v75, v75, v79
	v_cvt_pk_bf16_f32 v77, v74, v75
	v_mov_b64_e32 v[74:75], s[30:31]
	v_mad_i64_i32 v[74:75], s[34:35], v174, s7, v[74:75]
	v_lshl_add_u64 v[74:75], v[178:179], 1, v[74:75]
	global_store_dwordx2 v[74:75], v[76:77], off
